# attention epilogue norm_g loads hoisted; GLU epilogue Y loads hoisted; first two vmcnt waits after a GEMM unit epilogue relaxed past its stores
# speedup vs baseline: 1.0014x; 1.0014x over previous
; __device__ __forceinline__ int fresh_lane() { int l; asm volatile("v_mbcnt_lo_u32_b32 %0, -1, 0\n\tv_mbcnt_hi_u32_b32 %0, -1, %0" : "=v"(l)); return l; }
; #define PG8_STAGE(bufoff, gbase, voff) do { _Pragma("unroll") for (int _i = 0; _i < 2; ++_i) \
;         __builtin_amdgcn_global_load_lds((const unsigned*)((const char*)(gbase) + (voff)[_i]), (PG8_LAS unsigned*)(lds + (bufoff) + ldsw + _i * 8192), 16, 0, 0); } while (0)
; #define PG8_WAIT_V(n) asm volatile("s_waitcnt vmcnt(" #n ")" ::: "memory")
; #define PG8_BAR __builtin_amdgcn_s_barrier()
; template <class Epi, class Sched, bool ALIGN_EPI = false, bool SP2 = false, bool F16 = false>
; __device__ __forceinline__ void gemm_phase(PG8_LAS unsigned char* lds, const Gemm g, const Sched& S, const Epi& E) {
;     int tid_ = g.wave * 64 + fresh_lane(); asm volatile("" : "+v"(tid_));   const int tid = tid_, wid = __builtin_amdgcn_readfirstlane(tid >> 6), lane = tid & 63, wr = wid >> 2, wc = wid & 3, fr = lane & 15, fq = lane >> 4;
;     const int K = g.K, nt = K / BK;
;     unsigned voffA[2], voffB[2];
; #pragma unroll
;     for (int i = 0; i < 2; ++i) { int R, C; stage_rc(tid * 16 + i * 8192, R, C); const int Rb = Epi::PERM ? ((R & ~31) + perm32(R & 31)) : R;
;         voffA[i] = (unsigned)(R * K + C) * 2u; voffB[i] = (unsigned)(Rb * K + C) * 2u; }
;     const size_t kstep = (size_t)(BK * 2);
;     const size_t hstep = (size_t)HALF * K * 2;
;     const size_t tstep = 2 * hstep;
;     const unsigned ldsw = (unsigned)wid * 1024u;
;     const int aoff = lds_byte(wr * 64 + fr, fq * 8), boff = lds_byte(wc * 32 + fr, fq * 8);
;     ...
;     if constexpr (SP2) {
;         PG8_STAGE(PG8_SB(0, 0), cB, voffB); PG8_STAGE(PG8_SB(0, 1), cB + hstep, voffB); PG8_STAGE(PG8_SA(0, 0), cA, voffA); PG8_STAGE(PG8_SA(0, 1), cA + hstep, voffA);
;         if (wr == 1) PG8_BAR;
;         PG8_WAIT_V(2); PG8_BAR;
;         PG8_STAGE(PG8_SB(1, 0), cB + kstep, voffB); PG8_STAGE(PG8_SA(1, 0), cA + kstep, voffA); PG8_STAGE(PG8_SB(1, 1), cB + hstep + kstep, voffB);
;         PG8_WAIT_V(6); PG8_BAR;
.LBB0_501:
	s_sext_i32_i16 s15, s12
	s_add_u32 s12, s8, 0x1ee00000
	v_lshrrev_b32_e32 v18, 1, v16
	s_addc_u32 s13, s9, 0
	v_and_b32_e32 v18, 24, v18
	s_lshl_b32 s17, s17, 5
	v_and_b32_e32 v17, 15, v16
	v_lshlrev_b32_e32 v19, 1, v18
	v_lshlrev_b32_e32 v16, 2, v16
	s_and_b32 s20, s17, 0x60
	s_add_i32 m0, s59, 0x18000
	v_lshl_add_u64 v[8:9], v[8:9], 0, s[24:25]
	v_lshl_or_b32 v142, s18, 6, v17
	v_lshl_or_b32 v17, v17, 6, v19
	s_lshl_b32 s18, s18, 13
	v_and_b32_e32 v16, 32, v16
	s_lshl_b32 s17, s20, 7
	s_waitcnt vmcnt(2)
	s_barrier
	global_load_lds_dwordx4 v[8:9], off
	v_lshl_add_u64 v[6:7], v[6:7], 0, s[24:25]
	s_add_i32 m0, s59, 0x1a000
	s_add_i32 s63, s59, 0x8000
	s_add_i32 s64, s59, 0xa000
	v_bitop3_b32 v19, v17, s18, v16 bitop3:0xde
	global_load_lds_dwordx4 v[6:7], off
	v_lshl_add_u64 v[2:3], v[2:3], 0, s[24:25]
	s_mov_b32 m0, s63
	s_add_u32 s18, s44, 0x80080
	global_load_lds_dwordx4 v[2:3], off
	v_lshl_add_u64 v[2:3], v[4:5], 0, s[24:25]
	s_mov_b32 m0, s64
	s_addc_u32 s19, s45, 0
	global_load_lds_dwordx4 v[2:3], off
	s_add_i32 m0, s59, 0x1c000
	v_lshl_add_u64 v[2:3], s[18:19], 0, v[0:1]
	global_load_lds_dwordx4 v[2:3], off
	v_lshl_add_u64 v[2:3], s[18:19], 0, v[130:131]
	s_add_i32 m0, s59, 0x1e000
	s_cmpk_lt_u32 s16, 0x100
	global_load_lds_dwordx4 v[2:3], off
	v_lshlrev_b32_e32 v2, 15, v14
	v_and_b32_e32 v2, 0xffff0000, v2
	v_lshl_add_u32 v2, v13, 12, v2
	v_and_b32_e32 v3, 1, v14
	v_lshl_or_b32 v2, v3, 6, v2
	v_lshl_add_u32 v136, v15, 1, v2
	v_lshlrev_b32_e32 v2, 15, v10
	v_and_b32_e32 v2, 0xffff0000, v2
	s_waitcnt vmcnt(6)
	v_lshl_add_u32 v2, v11, 12, v2
	v_and_b32_e32 v3, 1, v10
	v_lshl_or_b32 v2, v3, 6, v2
	v_bitop3_b32 v143, v17, s17, v16 bitop3:0xde
	s_cselect_b64 s[16:17], -1, 0
	s_ashr_i32 s65, s37, 31
	v_or_b32_e32 v144, s20, v18
	v_mov_b32_e32 v137, v1
	v_lshl_add_u32 v138, v12, 1, v2
	v_mov_b32_e32 v139, v1
	s_mov_b32 s66, 0
	v_mov_b64_e32 v[140:141], s[80:81]
	v_add_u32_e32 v145, 0, v19
	s_barrier
	s_mov_b32 s100, 0
	s_branch .LBB0_504

; #define PG8_BAR __builtin_amdgcn_s_barrier()
; template <class Epi, class Sched, bool ALIGN_EPI = false, bool SP2 = false, bool F16 = false>
; __device__ __forceinline__ void gemm_phase(PG8_LAS unsigned char* lds, const Gemm g, const Sched& S, const Epi& E) {
;     ...
;         if (!has_next) break;
; #pragma unroll
;         for (int a = 0; a < 2; ++a)
; #pragma unroll
;             for (int b = 0; b < 2; ++b)
; #pragma unroll
;                 for (int m = 0; m < 4; ++m)
; #pragma unroll
;                     for (int n = 0; n < 2; ++n) acc[a][b][m][n] = (f32x4){0.f, 0.f, 0.f, 0.f};
;         cur = nxt; cA = nA; cB = nB; ++ui;
;         if constexpr (ALIGN_EPI) { if (wr == 1) PG8_BAR; }
;     }
.LBB0_503:
	s_andn2_b64 vcc, exec, s[14:15]
	s_mov_b32 s15, s18
	s_mov_b32 s14, s20
	s_mov_b64 s[44:45], s[40:41]
	s_mov_b64 s[42:43], s[26:27]
	s_cbranch_vccz .LBB0_513
	s_mov_b32 s100, 2

; #define PG8_STAGE(bufoff, gbase, voff) do { _Pragma("unroll") for (int _i = 0; _i < 2; ++_i) \
;         __builtin_amdgcn_global_load_lds((const unsigned*)((const char*)(gbase) + (voff)[_i]), (PG8_LAS unsigned*)(lds + (bufoff) + ldsw + _i * 8192), 16, 0, 0); } while (0)
; #define PG8_LDA(dst, b, h) do { _Pragma("unroll") for (int m = 0; m < 4; ++m) _Pragma("unroll") for (int k = 0; k < 2; ++k) dst[m][k] = *(const PG8_LAS bf16x8*)(lds + PG8_SA(b, h) + aoff + m * 2048 + k * 1024); } while (0)
; #define PG8_LDB(dst, b, h) do { _Pragma("unroll") for (int n = 0; n < 2; ++n) _Pragma("unroll") for (int k = 0; k < 2; ++k) dst[n][k] = *(const PG8_LAS bf16x8*)(lds + PG8_SB(b, h) + boff + n * 2048 + k * 1024); } while (0)
; #define PG8_MMA(ai, bj, At, Bt) do { __builtin_amdgcn_s_setprio(1); _Pragma("unroll") for (int m = 0; m < 4; ++m) _Pragma("unroll") for (int n = 0; n < 2; ++n) _Pragma("unroll") for (int k = 0; k < 2; ++k) \
;         acc[ai][bj][m][n] = pg8_mma<F16>(Bt[n][k], At[m][k], acc[ai][bj][m][n]); __builtin_amdgcn_s_setprio(0); } while (0)
; #define PG8_WAIT_V(n) asm volatile("s_waitcnt vmcnt(" #n ")" ::: "memory")
; #define PG8_WAIT_L(n) asm volatile("s_waitcnt lgkmcnt(" #n ")" ::: "memory")
; #define PG8_BAR __builtin_amdgcn_s_barrier()
; #define PG8_SCHED __builtin_amdgcn_sched_barrier(0)
; template <class Epi, class Sched, bool ALIGN_EPI = false, bool SP2 = false, bool F16 = false>
; __device__ __forceinline__ void gemm_phase(PG8_LAS unsigned char* lds, const Gemm g, const Sched& S, const Epi& E) {
;     ...
;             PG8_LDB(B0, 0, 0); PG8_LDB(B1, 0, 1); PG8_SCHED; PG8_LDA(At, 0, 0); PG8_STAGE(PG8_SA(1, 1), a1 + hstep, voffA);
;             PG8_WAIT_V(8); PG8_WAIT_L(0); PG8_BAR; PG8_MMA(0, 0, At, B0); PG8_MMA(0, 1, At, B1); PG8_BAR; PG8_SCHED;
;             PG8_LDA(At, 0, 1); PG8_STAGE(PG8_SB(0, 0), b2, voffB); PG8_STAGE(PG8_SB(0, 1), b2 + hstep, voffB); PG8_STAGE(PG8_SA(0, 0), a2, voffA);
.LBB0_507:
	s_add_u32 s44, s42, 0xfff80080
	s_addc_u32 s45, s43, -1
	s_add_i32 s72, 0, 0x10000
	s_cmp_eq_u32 s71, 28
	s_cselect_b32 s47, s21, s45
	s_cselect_b32 s46, s67, s44
	s_cselect_b32 s45, s19, s70
	s_cselect_b32 s44, s68, s69
	s_add_i32 s76, 0, 0x14000
	v_add_u32_e32 v158, s72, v143
	v_add_u32_e32 v174, s76, v143
	ds_read_b128 v[146:149], v158
	ds_read_b128 v[150:153], v158 offset:1024
	ds_read_b128 v[154:157], v158 offset:2048
	ds_read_b128 v[158:161], v158 offset:3072
	ds_read_b128 v[162:165], v174
	ds_read_b128 v[166:169], v174 offset:1024
	ds_read_b128 v[170:173], v174 offset:2048
	ds_read_b128 v[174:177], v174 offset:3072
	v_lshl_add_u64 v[210:211], s[42:43], 0, v[136:137]
	s_add_i32 m0, s59, 0xc000
	ds_read_b128 v[178:181], v145
	ds_read_b128 v[182:185], v145 offset:1024
	ds_read_b128 v[186:189], v145 offset:2048
	ds_read_b128 v[190:193], v145 offset:3072
	ds_read_b128 v[194:197], v145 offset:4096
	ds_read_b128 v[198:201], v145 offset:5120
	ds_read_b128 v[202:205], v145 offset:6144
	ds_read_b128 v[206:209], v145 offset:7168
	global_load_lds_dwordx4 v[210:211], off
	v_lshl_add_u64 v[210:211], s[42:43], 0, v[138:139]
	s_add_i32 m0, s59, 0xe000
	s_nop 0
	global_load_lds_dwordx4 v[210:211], off
	s_cmp_eq_u32 s100, 0
	s_cbranch_scc1 .Lur_ip_n0
	s_sub_u32 s100, s100, 1
	s_waitcnt vmcnt(24)
	s_branch .Lur_ip_d0
.Lur_ip_n0:
	s_waitcnt vmcnt(8)
.Lur_ip_d0:
	s_waitcnt lgkmcnt(0)
	s_barrier
	s_setprio 1
	s_waitcnt lgkmcnt(0)
	v_mfma_f32_16x16x32_bf16 v[126:129], v[146:149], v[178:181], v[126:129]
	v_mfma_f32_16x16x32_bf16 v[122:125], v[154:157], v[178:181], v[122:125]
	v_mfma_f32_16x16x32_bf16 v[118:121], v[146:149], v[186:189], v[118:121]
	v_mfma_f32_16x16x32_bf16 v[114:117], v[154:157], v[186:189], v[114:117]
	v_mfma_f32_16x16x32_bf16 v[102:105], v[146:149], v[194:197], v[102:105]
	v_mfma_f32_16x16x32_bf16 v[98:101], v[154:157], v[194:197], v[98:101]
	v_mfma_f32_16x16x32_bf16 v[86:89], v[146:149], v[202:205], v[86:89]
	v_mfma_f32_16x16x32_bf16 v[82:85], v[154:157], v[202:205], v[82:85]
	v_mfma_f32_16x16x32_bf16 v[126:129], v[150:153], v[182:185], v[126:129]
	v_mfma_f32_16x16x32_bf16 v[122:125], v[158:161], v[182:185], v[122:125]
	v_mfma_f32_16x16x32_bf16 v[118:121], v[150:153], v[190:193], v[118:121]
	v_mfma_f32_16x16x32_bf16 v[114:117], v[158:161], v[190:193], v[114:117]
	v_mfma_f32_16x16x32_bf16 v[102:105], v[150:153], v[198:201], v[102:105]
	v_mfma_f32_16x16x32_bf16 v[98:101], v[158:161], v[198:201], v[98:101]
	v_mfma_f32_16x16x32_bf16 v[86:89], v[150:153], v[206:209], v[86:89]
	v_mfma_f32_16x16x32_bf16 v[82:85], v[158:161], v[206:209], v[82:85]
	s_setprio 0
	s_setprio 1
	v_mfma_f32_16x16x32_bf16 v[110:113], v[162:165], v[178:181], v[110:113]
	v_mfma_f32_16x16x32_bf16 v[106:109], v[170:173], v[178:181], v[106:109]
	v_mfma_f32_16x16x32_bf16 v[94:97], v[162:165], v[186:189], v[94:97]
	v_mfma_f32_16x16x32_bf16 v[90:93], v[170:173], v[186:189], v[90:93]
	v_mfma_f32_16x16x32_bf16 v[78:81], v[162:165], v[194:197], v[78:81]
	v_mfma_f32_16x16x32_bf16 v[74:77], v[170:173], v[194:197], v[74:77]
	v_mfma_f32_16x16x32_bf16 v[70:73], v[162:165], v[202:205], v[70:73]
	v_mfma_f32_16x16x32_bf16 v[66:69], v[170:173], v[202:205], v[66:69]
	v_mfma_f32_16x16x32_bf16 v[110:113], v[166:169], v[182:185], v[110:113]
	v_mfma_f32_16x16x32_bf16 v[106:109], v[174:177], v[182:185], v[106:109]
	v_mfma_f32_16x16x32_bf16 v[94:97], v[166:169], v[190:193], v[94:97]
	v_mfma_f32_16x16x32_bf16 v[90:93], v[174:177], v[190:193], v[90:93]
	v_mfma_f32_16x16x32_bf16 v[78:81], v[166:169], v[198:201], v[78:81]
	v_mfma_f32_16x16x32_bf16 v[74:77], v[174:177], v[198:201], v[74:77]
	v_mfma_f32_16x16x32_bf16 v[70:73], v[166:169], v[206:209], v[70:73]
	v_mfma_f32_16x16x32_bf16 v[66:69], v[174:177], v[206:209], v[66:69]
	s_setprio 0
	s_barrier
	s_add_i32 s72, s72, s52
	v_lshl_add_u64 v[210:211], s[44:45], 0, v[0:1]
	s_mov_b32 m0, s72
	ds_read_b128 v[178:181], v145 offset:16384
	ds_read_b128 v[182:185], v145 offset:17408
	ds_read_b128 v[186:189], v145 offset:18432
	ds_read_b128 v[190:193], v145 offset:19456
	ds_read_b128 v[194:197], v145 offset:20480
	ds_read_b128 v[198:201], v145 offset:21504
	ds_read_b128 v[202:205], v145 offset:22528
	ds_read_b128 v[206:209], v145 offset:23552
	global_load_lds_dwordx4 v[210:211], off
	s_add_i32 m0, s72, 0x2000
	s_add_u32 s72, s44, 0x80000
	v_lshl_add_u64 v[214:215], s[44:45], 0, v[130:131]
	s_addc_u32 s73, s45, 0
	s_add_i32 s76, s76, s52
	global_load_lds_dwordx4 v[214:215], off
	v_lshl_add_u64 v[220:221], s[72:73], 0, v[0:1]
	s_mov_b32 m0, s76
	v_lshl_add_u64 v[222:223], s[46:47], 0, v[132:133]
	global_load_lds_dwordx4 v[220:221], off
	v_lshl_add_u64 v[220:221], s[72:73], 0, v[130:131]
	s_add_i32 m0, s76, 0x2000
	s_nop 0
	global_load_lds_dwordx4 v[220:221], off
	v_lshl_add_u64 v[220:221], s[46:47], 0, v[134:135]
	s_mov_b32 m0, s59
	s_nop 0
	global_load_lds_dwordx4 v[220:221], off
	s_mov_b32 m0, s60
	s_nop 0
	global_load_lds_dwordx4 v[222:223], off
	s_cmp_eq_u32 s100, 0
	s_cbranch_scc1 .Lur_ip_n1
	s_sub_u32 s100, s100, 1
	s_waitcnt vmcnt(24)
	s_branch .Lur_ip_d1

; #define PG8_STAGE(bufoff, gbase, voff) do { _Pragma("unroll") for (int _i = 0; _i < 2; ++_i) \
;         __builtin_amdgcn_global_load_lds((const unsigned*)((const char*)(gbase) + (voff)[_i]), (PG8_LAS unsigned*)(lds + (bufoff) + ldsw + _i * 8192), 16, 0, 0); } while (0)
; #define PG8_LDA(dst, b, h) do { _Pragma("unroll") for (int m = 0; m < 4; ++m) _Pragma("unroll") for (int k = 0; k < 2; ++k) dst[m][k] = *(const PG8_LAS bf16x8*)(lds + PG8_SA(b, h) + aoff + m * 2048 + k * 1024); } while (0)
; #define PG8_LDB(dst, b, h) do { _Pragma("unroll") for (int n = 0; n < 2; ++n) _Pragma("unroll") for (int k = 0; k < 2; ++k) dst[n][k] = *(const PG8_LAS bf16x8*)(lds + PG8_SB(b, h) + boff + n * 2048 + k * 1024); } while (0)
; #define PG8_MMA(ai, bj, At, Bt) do { __builtin_amdgcn_s_setprio(1); _Pragma("unroll") for (int m = 0; m < 4; ++m) _Pragma("unroll") for (int n = 0; n < 2; ++n) _Pragma("unroll") for (int k = 0; k < 2; ++k) \
;         acc[ai][bj][m][n] = pg8_mma<F16>(Bt[n][k], At[m][k], acc[ai][bj][m][n]); __builtin_amdgcn_s_setprio(0); } while (0)
; #define PG8_WAIT_V(n) asm volatile("s_waitcnt vmcnt(" #n ")" ::: "memory")
; #define PG8_WAIT_L(n) asm volatile("s_waitcnt lgkmcnt(" #n ")" ::: "memory")
; #define PG8_BAR __builtin_amdgcn_s_barrier()
; #define PG8_SCHED __builtin_amdgcn_sched_barrier(0)
; template <class Epi, class Sched, bool ALIGN_EPI = false, bool SP2 = false, bool F16 = false>
; __device__ __forceinline__ void gemm_phase(PG8_LAS unsigned char* lds, const Gemm g, const Sched& S, const Epi& E) {
;     ...
;             PG8_WAIT_V(8); PG8_WAIT_L(0); PG8_BAR; PG8_MMA(1, 0, At, B0); PG8_MMA(1, 1, At, B1); PG8_BAR; PG8_SCHED;
;             PG8_LDB(B0, 1, 0); PG8_LDB(B1, 1, 1); PG8_SCHED; PG8_LDA(At, 1, 0); PG8_STAGE(PG8_SA(0, 1), a2 + hstep, voffA);
;             PG8_WAIT_V(8); PG8_WAIT_L(0); PG8_BAR; PG8_MMA(0, 0, At, B0); PG8_MMA(0, 1, At, B1); PG8_BAR; PG8_SCHED;
.Lur_ip_d1:
	s_waitcnt lgkmcnt(0)
	s_barrier
	s_setprio 1
	s_waitcnt lgkmcnt(0)
	v_mfma_f32_16x16x32_bf16 v[62:65], v[146:149], v[178:181], v[62:65]
	v_mfma_f32_16x16x32_bf16 v[58:61], v[154:157], v[178:181], v[58:61]
	v_mfma_f32_16x16x32_bf16 v[54:57], v[146:149], v[186:189], v[54:57]
	v_mfma_f32_16x16x32_bf16 v[50:53], v[154:157], v[186:189], v[50:53]
	v_mfma_f32_16x16x32_bf16 v[38:41], v[146:149], v[194:197], v[38:41]
	v_mfma_f32_16x16x32_bf16 v[34:37], v[154:157], v[194:197], v[34:37]
	v_mfma_f32_16x16x32_bf16 v[22:25], v[146:149], v[202:205], v[22:25]
	v_mfma_f32_16x16x32_bf16 v[18:21], v[154:157], v[202:205], v[18:21]
	v_mfma_f32_16x16x32_bf16 v[62:65], v[150:153], v[182:185], v[62:65]
	v_mfma_f32_16x16x32_bf16 v[58:61], v[158:161], v[182:185], v[58:61]
	v_mfma_f32_16x16x32_bf16 v[54:57], v[150:153], v[190:193], v[54:57]
	v_mfma_f32_16x16x32_bf16 v[50:53], v[158:161], v[190:193], v[50:53]
	v_mfma_f32_16x16x32_bf16 v[38:41], v[150:153], v[198:201], v[38:41]
	v_mfma_f32_16x16x32_bf16 v[34:37], v[158:161], v[198:201], v[34:37]
	v_mfma_f32_16x16x32_bf16 v[22:25], v[150:153], v[206:209], v[22:25]
	v_mfma_f32_16x16x32_bf16 v[18:21], v[158:161], v[206:209], v[18:21]
	s_setprio 0
	s_setprio 1
	v_mfma_f32_16x16x32_bf16 v[46:49], v[162:165], v[178:181], v[46:49]
	v_mfma_f32_16x16x32_bf16 v[42:45], v[170:173], v[178:181], v[42:45]
	v_mfma_f32_16x16x32_bf16 v[30:33], v[162:165], v[186:189], v[30:33]
	v_mfma_f32_16x16x32_bf16 v[26:29], v[170:173], v[186:189], v[26:29]
	v_mfma_f32_16x16x32_bf16 v[14:17], v[162:165], v[194:197], v[14:17]
	v_mfma_f32_16x16x32_bf16 v[10:13], v[170:173], v[194:197], v[10:13]
	v_mfma_f32_16x16x32_bf16 v[6:9], v[162:165], v[202:205], v[6:9]
	v_mfma_f32_16x16x32_bf16 v[2:5], v[170:173], v[202:205], v[2:5]
	v_mfma_f32_16x16x32_bf16 v[46:49], v[166:169], v[182:185], v[46:49]
	v_mfma_f32_16x16x32_bf16 v[42:45], v[174:177], v[182:185], v[42:45]
	v_mfma_f32_16x16x32_bf16 v[30:33], v[166:169], v[190:193], v[30:33]
	v_mfma_f32_16x16x32_bf16 v[26:29], v[174:177], v[190:193], v[26:29]
	v_mfma_f32_16x16x32_bf16 v[14:17], v[166:169], v[198:201], v[14:17]
	v_mfma_f32_16x16x32_bf16 v[10:13], v[174:177], v[198:201], v[10:13]
	v_mfma_f32_16x16x32_bf16 v[6:9], v[166:169], v[206:209], v[6:9]
	v_mfma_f32_16x16x32_bf16 v[2:5], v[174:177], v[206:209], v[2:5]
	s_setprio 0
	s_barrier
	s_add_i32 s72, 0, 0x18000
	s_add_i32 s73, 0, 0x1c000
	v_add_u32_e32 v158, s72, v143
	v_add_u32_e32 v174, s73, v143
	ds_read_b128 v[146:149], v158
	ds_read_b128 v[150:153], v158 offset:1024
	ds_read_b128 v[154:157], v158 offset:2048
	ds_read_b128 v[158:161], v158 offset:3072
	ds_read_b128 v[162:165], v174
	ds_read_b128 v[166:169], v174 offset:1024
	ds_read_b128 v[170:173], v174 offset:2048
	ds_read_b128 v[174:177], v174 offset:3072
	s_add_u32 s46, s46, 0x80000
	s_addc_u32 s47, s47, 0
	s_mov_b32 m0, s61
	v_lshl_add_u64 v[224:225], s[46:47], 0, v[134:135]
	ds_read_b128 v[178:181], v145 offset:32768
	ds_read_b128 v[182:185], v145 offset:33792
	ds_read_b128 v[186:189], v145 offset:34816
	ds_read_b128 v[190:193], v145 offset:35840
	ds_read_b128 v[194:197], v145 offset:36864
	ds_read_b128 v[198:201], v145 offset:37888
	ds_read_b128 v[202:205], v145 offset:38912
	ds_read_b128 v[206:209], v145 offset:39936
	global_load_lds_dwordx4 v[224:225], off
	v_lshl_add_u64 v[224:225], s[46:47], 0, v[132:133]
	s_mov_b32 m0, s62
	s_nop 0
	global_load_lds_dwordx4 v[224:225], off
	s_waitcnt vmcnt(8)
	s_waitcnt lgkmcnt(0)
	s_barrier
	s_setprio 1
	s_waitcnt lgkmcnt(0)
	v_mfma_f32_16x16x32_bf16 v[126:129], v[146:149], v[178:181], v[126:129]
	v_mfma_f32_16x16x32_bf16 v[122:125], v[154:157], v[178:181], v[122:125]
	v_mfma_f32_16x16x32_bf16 v[118:121], v[146:149], v[186:189], v[118:121]
	v_mfma_f32_16x16x32_bf16 v[114:117], v[154:157], v[186:189], v[114:117]
	v_mfma_f32_16x16x32_bf16 v[102:105], v[146:149], v[194:197], v[102:105]
	v_mfma_f32_16x16x32_bf16 v[98:101], v[154:157], v[194:197], v[98:101]
	v_mfma_f32_16x16x32_bf16 v[86:89], v[146:149], v[202:205], v[86:89]
	v_mfma_f32_16x16x32_bf16 v[82:85], v[154:157], v[202:205], v[82:85]
	v_mfma_f32_16x16x32_bf16 v[126:129], v[150:153], v[182:185], v[126:129]
	v_mfma_f32_16x16x32_bf16 v[122:125], v[158:161], v[182:185], v[122:125]
	v_mfma_f32_16x16x32_bf16 v[118:121], v[150:153], v[190:193], v[118:121]
	v_mfma_f32_16x16x32_bf16 v[114:117], v[158:161], v[190:193], v[114:117]
	v_mfma_f32_16x16x32_bf16 v[102:105], v[150:153], v[198:201], v[102:105]
	v_mfma_f32_16x16x32_bf16 v[98:101], v[158:161], v[198:201], v[98:101]
	v_mfma_f32_16x16x32_bf16 v[86:89], v[150:153], v[206:209], v[86:89]
	v_mfma_f32_16x16x32_bf16 v[82:85], v[158:161], v[206:209], v[82:85]
	s_setprio 0
	s_setprio 1
	v_mfma_f32_16x16x32_bf16 v[110:113], v[162:165], v[178:181], v[110:113]
	v_mfma_f32_16x16x32_bf16 v[106:109], v[170:173], v[178:181], v[106:109]
	v_mfma_f32_16x16x32_bf16 v[94:97], v[162:165], v[186:189], v[94:97]
	v_mfma_f32_16x16x32_bf16 v[90:93], v[170:173], v[186:189], v[90:93]
	v_mfma_f32_16x16x32_bf16 v[78:81], v[162:165], v[194:197], v[78:81]
	v_mfma_f32_16x16x32_bf16 v[74:77], v[170:173], v[194:197], v[74:77]
	v_mfma_f32_16x16x32_bf16 v[70:73], v[162:165], v[202:205], v[70:73]
	v_mfma_f32_16x16x32_bf16 v[66:69], v[170:173], v[202:205], v[66:69]
	v_mfma_f32_16x16x32_bf16 v[110:113], v[166:169], v[182:185], v[110:113]
	v_mfma_f32_16x16x32_bf16 v[106:109], v[174:177], v[182:185], v[106:109]
	v_mfma_f32_16x16x32_bf16 v[94:97], v[166:169], v[190:193], v[94:97]
	v_mfma_f32_16x16x32_bf16 v[90:93], v[174:177], v[190:193], v[90:93]
	v_mfma_f32_16x16x32_bf16 v[78:81], v[166:169], v[198:201], v[78:81]
	v_mfma_f32_16x16x32_bf16 v[74:77], v[174:177], v[198:201], v[74:77]
	v_mfma_f32_16x16x32_bf16 v[70:73], v[166:169], v[206:209], v[70:73]
	v_mfma_f32_16x16x32_bf16 v[66:69], v[174:177], v[206:209], v[66:69]
	s_setprio 0
	s_barrier
; #define PG8_STAGE(bufoff, gbase, voff) do { _Pragma("unroll") for (int _i = 0; _i < 2; ++_i) \
;         __builtin_amdgcn_global_load_lds((const unsigned*)((const char*)(gbase) + (voff)[_i]), (PG8_LAS unsigned*)(lds + (bufoff) + ldsw + _i * 8192), 16, 0, 0); } while (0)
; #define PG8_LDA(dst, b, h) do { _Pragma("unroll") for (int m = 0; m < 4; ++m) _Pragma("unroll") for (int k = 0; k < 2; ++k) dst[m][k] = *(const PG8_LAS bf16x8*)(lds + PG8_SA(b, h) + aoff + m * 2048 + k * 1024); } while (0)
; #define PG8_MMA(ai, bj, At, Bt) do { __builtin_amdgcn_s_setprio(1); _Pragma("unroll") for (int m = 0; m < 4; ++m) _Pragma("unroll") for (int n = 0; n < 2; ++n) _Pragma("unroll") for (int k = 0; k < 2; ++k) \
;         acc[ai][bj][m][n] = pg8_mma<F16>(Bt[n][k], At[m][k], acc[ai][bj][m][n]); __builtin_amdgcn_s_setprio(0); } while (0)
; #define PG8_WAIT_V(n) asm volatile("s_waitcnt vmcnt(" #n ")" ::: "memory")
; #define PG8_WAIT_L(n) asm volatile("s_waitcnt lgkmcnt(" #n ")" ::: "memory")
; #define PG8_BAR __builtin_amdgcn_s_barrier()
; #define PG8_SCHED __builtin_amdgcn_sched_barrier(0)
; template <class Epi, class Sched, bool ALIGN_EPI = false, bool SP2 = false, bool F16 = false>
; __device__ __forceinline__ void gemm_phase(PG8_LAS unsigned char* lds, const Gemm g, const Sched& S, const Epi& E) {
;     ...
;             PG8_LDA(At, 1, 1); PG8_STAGE(PG8_SB(1, 0), b3, voffB); PG8_STAGE(PG8_SB(1, 1), b3 + hstep, voffB); PG8_STAGE(PG8_SA(1, 0), a3, voffA);
;             PG8_WAIT_V(8); PG8_WAIT_L(0); PG8_BAR; PG8_MMA(1, 0, At, B0); PG8_MMA(1, 1, At, B1); PG8_BAR; PG8_SCHED;
;     ...
;         if constexpr (ALIGN_EPI) { if (wr == 0) PG8_BAR; }
	s_add_i32 s46, s72, s52
	v_lshl_add_u64 v[210:211], v[210:211], 0, s[24:25]
	s_mov_b32 m0, s46
	ds_read_b128 v[178:181], v145 offset:49152
	ds_read_b128 v[182:185], v145 offset:50176
	ds_read_b128 v[186:189], v145 offset:51200
	ds_read_b128 v[190:193], v145 offset:52224
	ds_read_b128 v[194:197], v145 offset:53248
	ds_read_b128 v[198:201], v145 offset:54272
	ds_read_b128 v[202:205], v145 offset:55296
	ds_read_b128 v[206:209], v145 offset:56320
	global_load_lds_dwordx4 v[210:211], off
	s_add_i32 m0, s46, 0x2000
	s_add_u32 s44, s44, 0x80080
	v_lshl_add_u64 v[210:211], v[214:215], 0, s[24:25]
	s_addc_u32 s45, s45, 0
	s_add_i32 s46, s73, s52
	global_load_lds_dwordx4 v[210:211], off
	v_lshl_add_u64 v[210:211], s[44:45], 0, v[0:1]
	s_mov_b32 m0, s46
	s_nop 0
	global_load_lds_dwordx4 v[210:211], off
	v_lshl_add_u64 v[210:211], s[44:45], 0, v[130:131]
	s_add_i32 m0, s46, 0x2000
	s_nop 0
	global_load_lds_dwordx4 v[210:211], off
	v_lshl_add_u64 v[210:211], v[220:221], 0, s[24:25]
	s_mov_b32 m0, s63
	s_nop 0
	global_load_lds_dwordx4 v[210:211], off
	v_lshl_add_u64 v[210:211], v[222:223], 0, s[24:25]
	s_mov_b32 m0, s64
	s_nop 0
	global_load_lds_dwordx4 v[210:211], off
	s_waitcnt vmcnt(8)
	s_waitcnt lgkmcnt(0)
	s_barrier
	s_setprio 1
	s_waitcnt lgkmcnt(0)
	v_mfma_f32_16x16x32_bf16 v[62:65], v[146:149], v[178:181], v[62:65]
	v_mfma_f32_16x16x32_bf16 v[58:61], v[154:157], v[178:181], v[58:61]
	v_mfma_f32_16x16x32_bf16 v[54:57], v[146:149], v[186:189], v[54:57]
	v_mfma_f32_16x16x32_bf16 v[50:53], v[154:157], v[186:189], v[50:53]
	v_mfma_f32_16x16x32_bf16 v[38:41], v[146:149], v[194:197], v[38:41]
	v_mfma_f32_16x16x32_bf16 v[34:37], v[154:157], v[194:197], v[34:37]
	v_mfma_f32_16x16x32_bf16 v[22:25], v[146:149], v[202:205], v[22:25]
	v_mfma_f32_16x16x32_bf16 v[18:21], v[154:157], v[202:205], v[18:21]
	v_mfma_f32_16x16x32_bf16 v[62:65], v[150:153], v[182:185], v[62:65]
	v_mfma_f32_16x16x32_bf16 v[58:61], v[158:161], v[182:185], v[58:61]
	v_mfma_f32_16x16x32_bf16 v[54:57], v[150:153], v[190:193], v[54:57]
	v_mfma_f32_16x16x32_bf16 v[50:53], v[158:161], v[190:193], v[50:53]
	v_mfma_f32_16x16x32_bf16 v[38:41], v[150:153], v[198:201], v[38:41]
	v_mfma_f32_16x16x32_bf16 v[34:37], v[158:161], v[198:201], v[34:37]
	v_mfma_f32_16x16x32_bf16 v[22:25], v[150:153], v[206:209], v[22:25]
	v_mfma_f32_16x16x32_bf16 v[18:21], v[158:161], v[206:209], v[18:21]
	s_setprio 0
	s_setprio 1
	v_mfma_f32_16x16x32_bf16 v[46:49], v[162:165], v[178:181], v[46:49]
	v_mfma_f32_16x16x32_bf16 v[42:45], v[170:173], v[178:181], v[42:45]
	v_mfma_f32_16x16x32_bf16 v[30:33], v[162:165], v[186:189], v[30:33]
	v_mfma_f32_16x16x32_bf16 v[26:29], v[170:173], v[186:189], v[26:29]
	v_mfma_f32_16x16x32_bf16 v[14:17], v[162:165], v[194:197], v[14:17]
	v_mfma_f32_16x16x32_bf16 v[10:13], v[170:173], v[194:197], v[10:13]
	v_mfma_f32_16x16x32_bf16 v[6:9], v[162:165], v[202:205], v[6:9]
	v_mfma_f32_16x16x32_bf16 v[2:5], v[170:173], v[202:205], v[2:5]
	v_mfma_f32_16x16x32_bf16 v[46:49], v[166:169], v[182:185], v[46:49]
	v_mfma_f32_16x16x32_bf16 v[42:45], v[174:177], v[182:185], v[42:45]
	v_mfma_f32_16x16x32_bf16 v[30:33], v[166:169], v[190:193], v[30:33]
	v_mfma_f32_16x16x32_bf16 v[26:29], v[174:177], v[190:193], v[26:29]
	v_mfma_f32_16x16x32_bf16 v[14:17], v[166:169], v[198:201], v[14:17]
	v_mfma_f32_16x16x32_bf16 v[10:13], v[174:177], v[198:201], v[10:13]
	v_mfma_f32_16x16x32_bf16 v[6:9], v[166:169], v[206:209], v[6:9]
	v_mfma_f32_16x16x32_bf16 v[2:5], v[174:177], v[206:209], v[2:5]
	s_setprio 0
	s_barrier
	s_add_i32 s71, s71, 2
	s_add_u32 s42, s42, 0x100
	s_addc_u32 s43, s43, 0
	s_add_u32 s69, s69, 0x100
	s_addc_u32 s70, s70, 0
	s_cmp_gt_u32 s71, 29
	s_cbranch_scc0 .LBB0_507
	s_and_b64 vcc, exec, s[16:17]
	s_cbranch_vccz .LBB0_510
	s_barrier

; __device__ __forceinline__ float xor16_sum(float v) { const auto r = __builtin_amdgcn_permlane16_swap(__float_as_uint(v), __float_as_uint(v), false, false); return __uint_as_float(r[0]) + __uint_as_float(r[1]); }
; __device__ __forceinline__ float xor32_sum(float v) { const auto r = __builtin_amdgcn_permlane32_swap(__float_as_uint(v), __float_as_uint(v), false, false); return __uint_as_float(r[0]) + __uint_as_float(r[1]); }
; #define LAS __attribute__((address_space(3)))
; __device__ __forceinline__ void attn_phase(LAS unsigned char* lds, const bf16* PROJ, bf16* MIX, const float* lq1, const float* lk1, const float* lq2, const float* lk2,
;                                            const float* norm_g, float lambda_init, int G, int wave_s) {
;     ...
;             __syncthreads();
;             if (mi == 0) {
;                 float ss = 0.f;
; #pragma unroll
;                 for (int mt = 0; mt < 16; ++mt) { const f32x4 o1 = *(const LAS f32x4*)(XCH + ((wq * 16 + mt) * 64 + lane) * 16); const f32x4 o = O[mt] * inv - lam * o1; O[mt] = o;
;                     ss += (o.x * o.x + o.y * o.y) + (o.z * o.z + o.w * o.w); }
;                 ss = xor32_sum(xor16_sum(ss));
.LBB0_903:
	s_andn2_b64 vcc, exec, s[14:15]
	s_waitcnt lgkmcnt(0)
	s_barrier
	s_cbranch_vccnz .LBB0_883
	ds_read_b128 v[70:73], v68
	s_waitcnt lgkmcnt(0)
	v_pk_mul_f32 v[66:67], v[152:153], v[72:73]
	v_pk_mul_f32 v[70:71], v[150:151], v[70:71]
	v_pk_fma_f32 v[64:65], v[64:65], v[0:1], v[66:67] op_sel_hi:[1,0,1] neg_lo:[0,0,1] neg_hi:[0,0,1]
	v_pk_fma_f32 v[66:67], v[62:63], v[0:1], v[70:71] op_sel_hi:[1,0,1] neg_lo:[0,0,1] neg_hi:[0,0,1]
	ds_read_b128 v[70:73], v68 offset:1024
	v_mul_f32_e32 v62, v67, v67
	v_mul_f32_e32 v63, v65, v65
	v_fmac_f32_e32 v62, v66, v66
	v_fmac_f32_e32 v63, v64, v64
	v_add_f32_e32 v69, v62, v63
	s_waitcnt lgkmcnt(0)
	v_pk_mul_f32 v[62:63], v[152:153], v[72:73]
	v_pk_mul_f32 v[70:71], v[150:151], v[70:71]
	v_pk_fma_f32 v[60:61], v[60:61], v[0:1], v[62:63] op_sel_hi:[1,0,1] neg_lo:[0,0,1] neg_hi:[0,0,1]
	v_pk_fma_f32 v[62:63], v[58:59], v[0:1], v[70:71] op_sel_hi:[1,0,1] neg_lo:[0,0,1] neg_hi:[0,0,1]
	ds_read_b128 v[70:73], v68 offset:2048
	v_mul_f32_e32 v58, v63, v63
	v_mul_f32_e32 v59, v61, v61
	v_fmac_f32_e32 v58, v62, v62
	v_fmac_f32_e32 v59, v60, v60
	v_add_f32_e32 v58, v58, v59
	v_add_f32_e32 v69, v69, v58
	s_waitcnt lgkmcnt(0)
	v_pk_mul_f32 v[58:59], v[152:153], v[72:73]
	v_pk_mul_f32 v[70:71], v[150:151], v[70:71]
	v_pk_fma_f32 v[56:57], v[56:57], v[0:1], v[58:59] op_sel_hi:[1,0,1] neg_lo:[0,0,1] neg_hi:[0,0,1]
	v_pk_fma_f32 v[58:59], v[54:55], v[0:1], v[70:71] op_sel_hi:[1,0,1] neg_lo:[0,0,1] neg_hi:[0,0,1]
	ds_read_b128 v[70:73], v68 offset:3072
	v_mul_f32_e32 v54, v59, v59
	v_mul_f32_e32 v55, v57, v57
	v_fmac_f32_e32 v54, v58, v58
	v_fmac_f32_e32 v55, v56, v56
	v_add_f32_e32 v54, v54, v55
	v_add_f32_e32 v69, v69, v54
	s_waitcnt lgkmcnt(0)
	v_pk_mul_f32 v[54:55], v[152:153], v[72:73]
	v_pk_mul_f32 v[70:71], v[150:151], v[70:71]
	v_pk_fma_f32 v[52:53], v[52:53], v[0:1], v[54:55] op_sel_hi:[1,0,1] neg_lo:[0,0,1] neg_hi:[0,0,1]
	v_pk_fma_f32 v[54:55], v[50:51], v[0:1], v[70:71] op_sel_hi:[1,0,1] neg_lo:[0,0,1] neg_hi:[0,0,1]
	ds_read_b128 v[70:73], v68 offset:4096
	v_mul_f32_e32 v50, v55, v55
	v_mul_f32_e32 v51, v53, v53
	v_fmac_f32_e32 v50, v54, v54
	v_fmac_f32_e32 v51, v52, v52
	v_add_f32_e32 v50, v50, v51
	v_add_f32_e32 v69, v69, v50
	s_waitcnt lgkmcnt(0)
	v_pk_mul_f32 v[50:51], v[152:153], v[72:73]
	v_pk_mul_f32 v[70:71], v[150:151], v[70:71]
	v_pk_fma_f32 v[48:49], v[48:49], v[0:1], v[50:51] op_sel_hi:[1,0,1] neg_lo:[0,0,1] neg_hi:[0,0,1]
	v_pk_fma_f32 v[50:51], v[46:47], v[0:1], v[70:71] op_sel_hi:[1,0,1] neg_lo:[0,0,1] neg_hi:[0,0,1]
	ds_read_b128 v[70:73], v68 offset:5120
	v_mul_f32_e32 v46, v51, v51
	v_mul_f32_e32 v47, v49, v49
	v_fmac_f32_e32 v46, v50, v50
	v_fmac_f32_e32 v47, v48, v48
	v_add_f32_e32 v46, v46, v47
	v_add_f32_e32 v69, v69, v46
	s_waitcnt lgkmcnt(0)
	v_pk_mul_f32 v[46:47], v[152:153], v[72:73]
	v_pk_mul_f32 v[70:71], v[150:151], v[70:71]
	v_pk_fma_f32 v[44:45], v[44:45], v[0:1], v[46:47] op_sel_hi:[1,0,1] neg_lo:[0,0,1] neg_hi:[0,0,1]
	v_pk_fma_f32 v[46:47], v[42:43], v[0:1], v[70:71] op_sel_hi:[1,0,1] neg_lo:[0,0,1] neg_hi:[0,0,1]
	ds_read_b128 v[70:73], v68 offset:6144
	v_mul_f32_e32 v42, v47, v47
	v_mul_f32_e32 v43, v45, v45
	v_fmac_f32_e32 v42, v46, v46
	v_fmac_f32_e32 v43, v44, v44
	v_add_f32_e32 v42, v42, v43
	v_add_f32_e32 v69, v69, v42
	s_waitcnt lgkmcnt(0)
	v_pk_mul_f32 v[42:43], v[152:153], v[72:73]
	v_pk_mul_f32 v[70:71], v[150:151], v[70:71]
	v_pk_fma_f32 v[40:41], v[40:41], v[0:1], v[42:43] op_sel_hi:[1,0,1] neg_lo:[0,0,1] neg_hi:[0,0,1]
	v_pk_fma_f32 v[42:43], v[38:39], v[0:1], v[70:71] op_sel_hi:[1,0,1] neg_lo:[0,0,1] neg_hi:[0,0,1]
	ds_read_b128 v[70:73], v68 offset:7168
	v_mul_f32_e32 v38, v43, v43
	v_mul_f32_e32 v39, v41, v41
	v_fmac_f32_e32 v38, v42, v42
	v_fmac_f32_e32 v39, v40, v40
	v_add_f32_e32 v38, v38, v39
	v_add_f32_e32 v69, v69, v38
	s_waitcnt lgkmcnt(0)
	v_pk_mul_f32 v[38:39], v[152:153], v[72:73]
	v_pk_mul_f32 v[70:71], v[150:151], v[70:71]
	v_pk_fma_f32 v[36:37], v[36:37], v[0:1], v[38:39] op_sel_hi:[1,0,1] neg_lo:[0,0,1] neg_hi:[0,0,1]
	v_pk_fma_f32 v[38:39], v[34:35], v[0:1], v[70:71] op_sel_hi:[1,0,1] neg_lo:[0,0,1] neg_hi:[0,0,1]
	ds_read_b128 v[70:73], v68 offset:8192
	v_mul_f32_e32 v34, v39, v39
	v_mul_f32_e32 v35, v37, v37
	v_fmac_f32_e32 v34, v38, v38
	v_fmac_f32_e32 v35, v36, v36
	v_add_f32_e32 v34, v34, v35
	v_add_f32_e32 v69, v69, v34
	s_waitcnt lgkmcnt(0)
	v_pk_mul_f32 v[34:35], v[152:153], v[72:73]
	v_pk_mul_f32 v[70:71], v[150:151], v[70:71]
	v_pk_fma_f32 v[32:33], v[32:33], v[0:1], v[34:35] op_sel_hi:[1,0,1] neg_lo:[0,0,1] neg_hi:[0,0,1]
	v_pk_fma_f32 v[34:35], v[30:31], v[0:1], v[70:71] op_sel_hi:[1,0,1] neg_lo:[0,0,1] neg_hi:[0,0,1]
	ds_read_b128 v[70:73], v68 offset:9216
	v_mul_f32_e32 v30, v35, v35
	v_mul_f32_e32 v31, v33, v33
	v_fmac_f32_e32 v30, v34, v34
	v_fmac_f32_e32 v31, v32, v32
	v_add_f32_e32 v30, v30, v31
	v_add_f32_e32 v69, v69, v30
	s_waitcnt lgkmcnt(0)
	v_pk_mul_f32 v[30:31], v[152:153], v[72:73]
	v_pk_mul_f32 v[70:71], v[150:151], v[70:71]
	v_pk_fma_f32 v[28:29], v[28:29], v[0:1], v[30:31] op_sel_hi:[1,0,1] neg_lo:[0,0,1] neg_hi:[0,0,1]
	v_pk_fma_f32 v[30:31], v[26:27], v[0:1], v[70:71] op_sel_hi:[1,0,1] neg_lo:[0,0,1] neg_hi:[0,0,1]
	ds_read_b128 v[70:73], v68 offset:10240
	v_mul_f32_e32 v26, v31, v31
	v_mul_f32_e32 v27, v29, v29
	v_fmac_f32_e32 v26, v30, v30
	v_fmac_f32_e32 v27, v28, v28
	v_add_f32_e32 v26, v26, v27
	v_add_f32_e32 v69, v69, v26
	s_waitcnt lgkmcnt(0)
; __device__ __forceinline__ float xor16_sum(float v) { const auto r = __builtin_amdgcn_permlane16_swap(__float_as_uint(v), __float_as_uint(v), false, false); return __uint_as_float(r[0]) + __uint_as_float(r[1]); }
; __device__ __forceinline__ float xor32_sum(float v) { const auto r = __builtin_amdgcn_permlane32_swap(__float_as_uint(v), __float_as_uint(v), false, false); return __uint_as_float(r[0]) + __uint_as_float(r[1]); }
; #define LAS __attribute__((address_space(3)))
; __device__ __forceinline__ void attn_phase(LAS unsigned char* lds, const bf16* PROJ, bf16* MIX, const float* lq1, const float* lk1, const float* lq2, const float* lk2,
;                                            const float* norm_g, float lambda_init, int G, int wave_s) {
;     ...
;                 for (int mt = 0; mt < 16; ++mt) { const f32x4 o1 = *(const LAS f32x4*)(XCH + ((wq * 16 + mt) * 64 + lane) * 16); const f32x4 o = O[mt] * inv - lam * o1; O[mt] = o;
;                     ss += (o.x * o.x + o.y * o.y) + (o.z * o.z + o.w * o.w); }
;                 ss = xor32_sum(xor16_sum(ss));
;                 const float rs = __builtin_amdgcn_rsqf(ss * (1.0f / 256.0f) + LN_EPS) * (1.0f - lambda_init);
;                 bf16* orow = MIX + (size_t)(b * SEQ + 64 * qb + qloc) * DM + 1024 + h * 256 + 4 * q4;
; #pragma unroll
;                 for (int mt = 0; mt < 16; ++mt) { const f32x4 g = *(const f32x4*)(norm_g + 16 * mt + 4 * q4); const f32x4 o = O[mt] * rs * g;
	v_pk_mul_f32 v[26:27], v[152:153], v[72:73]
	v_pk_mul_f32 v[70:71], v[150:151], v[70:71]
	v_pk_fma_f32 v[24:25], v[24:25], v[0:1], v[26:27] op_sel_hi:[1,0,1] neg_lo:[0,0,1] neg_hi:[0,0,1]
	v_pk_fma_f32 v[26:27], v[22:23], v[0:1], v[70:71] op_sel_hi:[1,0,1] neg_lo:[0,0,1] neg_hi:[0,0,1]
	ds_read_b128 v[70:73], v68 offset:11264
	v_mul_f32_e32 v22, v27, v27
	v_mul_f32_e32 v23, v25, v25
	v_fmac_f32_e32 v22, v26, v26
	v_fmac_f32_e32 v23, v24, v24
	v_add_f32_e32 v22, v22, v23
	v_add_f32_e32 v69, v69, v22
	s_waitcnt lgkmcnt(0)
	v_pk_mul_f32 v[22:23], v[152:153], v[72:73]
	v_pk_mul_f32 v[70:71], v[150:151], v[70:71]
	v_pk_fma_f32 v[16:17], v[16:17], v[0:1], v[22:23] op_sel_hi:[1,0,1] neg_lo:[0,0,1] neg_hi:[0,0,1]
	v_pk_fma_f32 v[22:23], v[14:15], v[0:1], v[70:71] op_sel_hi:[1,0,1] neg_lo:[0,0,1] neg_hi:[0,0,1]
	ds_read_b128 v[70:73], v68 offset:12288
	v_mul_f32_e32 v14, v23, v23
	v_mul_f32_e32 v15, v17, v17
	v_fmac_f32_e32 v14, v22, v22
	v_fmac_f32_e32 v15, v16, v16
	v_add_f32_e32 v14, v14, v15
	s_waitcnt lgkmcnt(0)
	v_pk_mul_f32 v[70:71], v[150:151], v[70:71]
	v_add_f32_e32 v69, v69, v14
	v_pk_mul_f32 v[14:15], v[152:153], v[72:73]
	v_pk_fma_f32 v[18:19], v[18:19], v[0:1], v[70:71] op_sel_hi:[1,0,1] neg_lo:[0,0,1] neg_hi:[0,0,1]
	ds_read_b128 v[70:73], v68 offset:13312
	v_pk_fma_f32 v[14:15], v[20:21], v[0:1], v[14:15] op_sel_hi:[1,0,1] neg_lo:[0,0,1] neg_hi:[0,0,1]
	v_mul_f32_e32 v20, v19, v19
	v_mul_f32_e32 v21, v15, v15
	v_fmac_f32_e32 v20, v18, v18
	v_fmac_f32_e32 v21, v14, v14
	v_add_f32_e32 v20, v20, v21
	v_add_f32_e32 v69, v69, v20
	s_waitcnt lgkmcnt(0)
	v_pk_mul_f32 v[20:21], v[152:153], v[72:73]
	v_pk_mul_f32 v[70:71], v[150:151], v[70:71]
	v_pk_fma_f32 v[12:13], v[12:13], v[0:1], v[20:21] op_sel_hi:[1,0,1] neg_lo:[0,0,1] neg_hi:[0,0,1]
	v_pk_fma_f32 v[10:11], v[10:11], v[0:1], v[70:71] op_sel_hi:[1,0,1] neg_lo:[0,0,1] neg_hi:[0,0,1]
	v_mul_f32_e32 v21, v13, v13
	v_mul_f32_e32 v20, v11, v11
	v_fmac_f32_e32 v20, v10, v10
	v_fmac_f32_e32 v21, v12, v12
	v_add_f32_e32 v20, v20, v21
	v_add_f32_e32 v72, v69, v20
	ds_read_b128 v[68:71], v68 offset:14336
	s_waitcnt lgkmcnt(0)
	v_pk_mul_f32 v[20:21], v[152:153], v[70:71]
	v_pk_mul_f32 v[68:69], v[150:151], v[68:69]
	v_pk_fma_f32 v[8:9], v[8:9], v[0:1], v[20:21] op_sel_hi:[1,0,1] neg_lo:[0,0,1] neg_hi:[0,0,1]
	v_pk_fma_f32 v[6:7], v[6:7], v[0:1], v[68:69] op_sel_hi:[1,0,1] neg_lo:[0,0,1] neg_hi:[0,0,1]
	v_mul_f32_e32 v21, v9, v9
	v_mul_f32_e32 v20, v7, v7
	v_fmac_f32_e32 v20, v6, v6
	v_fmac_f32_e32 v21, v8, v8
	v_add_f32_e32 v20, v20, v21
	v_add_f32_e32 v72, v72, v20
	v_add_u32_e32 v20, s73, v170
	ds_read_b128 v[68:71], v20
	s_waitcnt lgkmcnt(0)
	v_pk_mul_f32 v[20:21], v[152:153], v[70:71]
	v_pk_mul_f32 v[68:69], v[150:151], v[68:69]
	v_pk_fma_f32 v[20:21], v[4:5], v[0:1], v[20:21] op_sel_hi:[1,0,1] neg_lo:[0,0,1] neg_hi:[0,0,1]
	v_pk_fma_f32 v[68:69], v[2:3], v[0:1], v[68:69] op_sel_hi:[1,0,1] neg_lo:[0,0,1] neg_hi:[0,0,1]
	v_mul_f32_e32 v2, v21, v21
	v_mul_f32_e32 v0, v69, v69
	v_fmac_f32_e32 v0, v68, v68
	v_fmac_f32_e32 v2, v20, v20
	v_add_f32_e32 v0, v0, v2
	v_add_f32_e32 v0, v72, v0
	v_mov_b32_e32 v2, v0
	s_nop 1
	v_permlane16_swap_b32_e32 v0, v2
	v_add_f32_e32 v0, v0, v2
	v_mov_b32_e32 v2, v0
	s_nop 1
	v_permlane32_swap_b32_e32 v0, v2
	v_add_f32_e32 v0, v0, v2
	v_or_b32_e32 v2, s85, v214
	v_ashrrev_i32_e32 v3, 31, v2
	v_lshlrev_b64 v[2:3], 12, v[2:3]
	v_lshl_add_u64 v[70:71], v[160:161], 0, v[2:3]
	global_load_dwordx4 v[82:85], v[154:155], off
	global_load_dwordx4 v[86:89], v[154:155], off offset:64
	global_load_dwordx4 v[90:93], v[154:155], off offset:128
	global_load_dwordx4 v[94:97], v[154:155], off offset:192
	global_load_dwordx4 v[98:101], v[154:155], off offset:256
	global_load_dwordx4 v[102:105], v[154:155], off offset:320
	global_load_dwordx4 v[106:109], v[154:155], off offset:384
	global_load_dwordx4 v[110:113], v[154:155], off offset:448
	global_load_dwordx4 v[114:117], v[154:155], off offset:512
	global_load_dwordx4 v[118:121], v[154:155], off offset:576
	global_load_dwordx4 v[122:125], v[154:155], off offset:640
	global_load_dwordx4 v[126:129], v[154:155], off offset:704
	global_load_dwordx4 v[130:133], v[154:155], off offset:768
	global_load_dwordx4 v[134:137], v[154:155], off offset:832
	global_load_dwordx4 v[228:231], v[154:155], off offset:896
	global_load_dwordx4 v[232:235], v[154:155], off offset:960
	v_fmamk_f32 v0, v0, 0x3b800000, v216
	v_rsq_f32_e32 v0, v0
	s_nop 0
	v_mul_f32_e32 v0, v171, v0
	v_pk_mul_f32 v[66:67], v[66:67], v[0:1] op_sel_hi:[1,0]
	v_pk_mul_f32 v[64:65], v[64:65], v[0:1] op_sel_hi:[1,0]
	v_pk_mul_f32 v[62:63], v[62:63], v[0:1] op_sel_hi:[1,0]
	v_pk_mul_f32 v[60:61], v[60:61], v[0:1] op_sel_hi:[1,0]
	v_pk_mul_f32 v[58:59], v[58:59], v[0:1] op_sel_hi:[1,0]
	v_pk_mul_f32 v[56:57], v[56:57], v[0:1] op_sel_hi:[1,0]
	v_pk_mul_f32 v[54:55], v[54:55], v[0:1] op_sel_hi:[1,0]
	v_pk_mul_f32 v[52:53], v[52:53], v[0:1] op_sel_hi:[1,0]
	v_pk_mul_f32 v[50:51], v[50:51], v[0:1] op_sel_hi:[1,0]
	v_pk_mul_f32 v[48:49], v[48:49], v[0:1] op_sel_hi:[1,0]
	v_pk_mul_f32 v[46:47], v[46:47], v[0:1] op_sel_hi:[1,0]
	v_pk_mul_f32 v[44:45], v[44:45], v[0:1] op_sel_hi:[1,0]
	v_pk_mul_f32 v[42:43], v[42:43], v[0:1] op_sel_hi:[1,0]
	v_pk_mul_f32 v[40:41], v[40:41], v[0:1] op_sel_hi:[1,0]
	v_pk_mul_f32 v[38:39], v[38:39], v[0:1] op_sel_hi:[1,0]
	v_pk_mul_f32 v[36:37], v[36:37], v[0:1] op_sel_hi:[1,0]
	v_pk_mul_f32 v[34:35], v[34:35], v[0:1] op_sel_hi:[1,0]
	v_pk_mul_f32 v[32:33], v[32:33], v[0:1] op_sel_hi:[1,0]
	v_pk_mul_f32 v[30:31], v[30:31], v[0:1] op_sel_hi:[1,0]
	v_pk_mul_f32 v[28:29], v[28:29], v[0:1] op_sel_hi:[1,0]
	v_pk_mul_f32 v[26:27], v[26:27], v[0:1] op_sel_hi:[1,0]
	v_pk_mul_f32 v[24:25], v[24:25], v[0:1] op_sel_hi:[1,0]
	v_pk_mul_f32 v[22:23], v[22:23], v[0:1] op_sel_hi:[1,0]
	v_pk_mul_f32 v[16:17], v[16:17], v[0:1] op_sel_hi:[1,0]
	v_pk_mul_f32 v[14:15], v[14:15], v[0:1] op_sel_hi:[1,0]
	v_pk_mul_f32 v[10:11], v[10:11], v[0:1] op_sel_hi:[1,0]
	v_pk_mul_f32 v[12:13], v[12:13], v[0:1] op_sel_hi:[1,0]
	v_pk_mul_f32 v[6:7], v[6:7], v[0:1] op_sel_hi:[1,0]
	v_pk_mul_f32 v[8:9], v[8:9], v[0:1] op_sel_hi:[1,0]
	s_waitcnt vmcnt(0)
; __device__ __forceinline__ unsigned pk2(float lo, float hi) { const f32x2 v = {lo, hi}; const bf16x2_n b = __builtin_convertvector(v, bf16x2_n); return __builtin_bit_cast(unsigned, b); }
; __device__ __forceinline__ void attn_phase(LAS unsigned char* lds, const bf16* PROJ, bf16* MIX, const float* lq1, const float* lk1, const float* lq2, const float* lk2,
;                                            const float* norm_g, float lambda_init, int G, int wave_s) {
;     ...
;                 bf16* orow = MIX + (size_t)(b * SEQ + 64 * qb + qloc) * DM + 1024 + h * 256 + 4 * q4;
; #pragma unroll
;                 for (int mt = 0; mt < 16; ++mt) { const f32x4 g = *(const f32x4*)(norm_g + 16 * mt + 4 * q4); const f32x4 o = O[mt] * rs * g;
;                     v2u wv; wv.x = pk2(o.x, o.y); wv.y = pk2(o.z, o.w); *(v2u*)(orow + 16 * mt) = wv; }
	v_pk_mul_f32 v[4:5], v[84:85], v[64:65]
	v_pk_mul_f32 v[2:3], v[82:83], v[66:67]
	s_nop 0
	v_cvt_pk_bf16_f32 v2, v2, v3
	v_cvt_pk_bf16_f32 v3, v4, v5
	global_store_dwordx2 v[70:71], v[2:3], off offset:2048
	v_pk_mul_f32 v[4:5], v[88:89], v[60:61]
	v_pk_mul_f32 v[2:3], v[86:87], v[62:63]
	s_nop 0
	v_cvt_pk_bf16_f32 v2, v2, v3
	v_cvt_pk_bf16_f32 v3, v4, v5
	global_store_dwordx2 v[70:71], v[2:3], off offset:2080
	v_pk_mul_f32 v[4:5], v[92:93], v[56:57]
	v_pk_mul_f32 v[2:3], v[90:91], v[58:59]
	s_nop 0
	v_cvt_pk_bf16_f32 v2, v2, v3
	v_cvt_pk_bf16_f32 v3, v4, v5
	global_store_dwordx2 v[70:71], v[2:3], off offset:2112
	v_pk_mul_f32 v[4:5], v[96:97], v[52:53]
	v_pk_mul_f32 v[2:3], v[94:95], v[54:55]
	s_nop 0
	v_cvt_pk_bf16_f32 v2, v2, v3
	v_cvt_pk_bf16_f32 v3, v4, v5
	global_store_dwordx2 v[70:71], v[2:3], off offset:2144
	v_pk_mul_f32 v[4:5], v[100:101], v[48:49]
	v_pk_mul_f32 v[2:3], v[98:99], v[50:51]
	s_nop 0
	v_cvt_pk_bf16_f32 v2, v2, v3
	v_cvt_pk_bf16_f32 v3, v4, v5
	global_store_dwordx2 v[70:71], v[2:3], off offset:2176
	v_pk_mul_f32 v[4:5], v[44:45], v[104:105]
	v_pk_mul_f32 v[2:3], v[46:47], v[102:103]
	s_nop 0
	v_cvt_pk_bf16_f32 v2, v2, v3
	v_cvt_pk_bf16_f32 v3, v4, v5
	global_store_dwordx2 v[70:71], v[2:3], off offset:2208
	v_pk_mul_f32 v[4:5], v[40:41], v[108:109]
	v_pk_mul_f32 v[2:3], v[42:43], v[106:107]
	s_nop 0
	v_cvt_pk_bf16_f32 v2, v2, v3
	v_cvt_pk_bf16_f32 v3, v4, v5
	global_store_dwordx2 v[70:71], v[2:3], off offset:2240
	v_pk_mul_f32 v[4:5], v[36:37], v[112:113]
	v_pk_mul_f32 v[2:3], v[38:39], v[110:111]
	s_nop 0
	v_cvt_pk_bf16_f32 v2, v2, v3
	v_cvt_pk_bf16_f32 v3, v4, v5
	global_store_dwordx2 v[70:71], v[2:3], off offset:2272
	v_pk_mul_f32 v[4:5], v[32:33], v[116:117]
	v_pk_mul_f32 v[2:3], v[34:35], v[114:115]
	s_nop 0
	v_cvt_pk_bf16_f32 v2, v2, v3
	v_cvt_pk_bf16_f32 v3, v4, v5
	global_store_dwordx2 v[70:71], v[2:3], off offset:2304
	v_pk_mul_f32 v[4:5], v[28:29], v[120:121]
	v_pk_mul_f32 v[2:3], v[30:31], v[118:119]
	s_nop 0
	v_cvt_pk_bf16_f32 v2, v2, v3
	v_cvt_pk_bf16_f32 v3, v4, v5
	global_store_dwordx2 v[70:71], v[2:3], off offset:2336
	v_pk_mul_f32 v[4:5], v[24:25], v[124:125]
	v_pk_mul_f32 v[2:3], v[26:27], v[122:123]
	s_nop 0
	v_cvt_pk_bf16_f32 v2, v2, v3
	v_cvt_pk_bf16_f32 v3, v4, v5
	global_store_dwordx2 v[70:71], v[2:3], off offset:2368
	v_pk_mul_f32 v[4:5], v[16:17], v[128:129]
	v_pk_mul_f32 v[2:3], v[22:23], v[126:127]
	v_pk_mul_f32 v[16:17], v[18:19], v[0:1] op_sel_hi:[1,0]
	v_cvt_pk_bf16_f32 v2, v2, v3
	v_cvt_pk_bf16_f32 v3, v4, v5
	global_store_dwordx2 v[70:71], v[2:3], off offset:2400
	v_pk_mul_f32 v[4:5], v[14:15], v[132:133]
	v_pk_mul_f32 v[2:3], v[16:17], v[130:131]
	s_nop 0
	v_cvt_pk_bf16_f32 v2, v2, v3
	v_cvt_pk_bf16_f32 v3, v4, v5
	global_store_dwordx2 v[70:71], v[2:3], off offset:2432
	v_pk_mul_f32 v[4:5], v[12:13], v[136:137]
	v_pk_mul_f32 v[2:3], v[10:11], v[134:135]
	s_nop 0
	v_cvt_pk_bf16_f32 v2, v2, v3
	v_cvt_pk_bf16_f32 v3, v4, v5
	global_store_dwordx2 v[70:71], v[2:3], off offset:2464
	v_pk_mul_f32 v[4:5], v[8:9], v[230:231]
	v_pk_mul_f32 v[2:3], v[6:7], v[228:229]
	v_pk_mul_f32 v[6:7], v[68:69], v[0:1] op_sel_hi:[1,0]
	v_cvt_pk_bf16_f32 v2, v2, v3
	v_cvt_pk_bf16_f32 v3, v4, v5
	global_store_dwordx2 v[70:71], v[2:3], off offset:2496
	v_pk_mul_f32 v[8:9], v[20:21], v[0:1] op_sel_hi:[1,0]
	v_pk_mul_f32 v[2:3], v[6:7], v[232:233]
	v_pk_mul_f32 v[4:5], v[8:9], v[234:235]
	v_cvt_pk_bf16_f32 v2, v2, v3
	v_cvt_pk_bf16_f32 v3, v4, v5
	global_store_dwordx2 v[70:71], v[2:3], off offset:2528
	s_branch .LBB0_883

; __device__ __forceinline__ unsigned cvt_pk_bf16(float lo, float hi) { const pg8_f32x2 v = {lo, hi}; const pg8_bf16x2 b = __builtin_convertvector(v, pg8_bf16x2); return __builtin_bit_cast(unsigned, b); }
; __device__ __forceinline__ float ep_sigmoid(float x) { return __builtin_amdgcn_rcpf(1.0f + __expf(-x)); }
; __device__ __forceinline__ float ep_lo(unsigned w) { return __uint_as_float(w << 16); }
; __device__ __forceinline__ float ep_hi(unsigned w) { return __uint_as_float(w & 0xffff0000u); }
;     __device__ __forceinline__ void operator()(const f32x4 (&acc)[2][2][4][2], const Unit& u, int wr, int wc, int fr, int fq) const {
;     ...
;             for (int m = 0; m < 4; ++m) { const size_t row = (size_t)(row0 + ai * HALF + m * 16);
; #pragma unroll
;                 for (int bj = 0; bj < 2; ++bj) { const f32x4 v0 = acc[ai][bj][m][0], v1 = acc[ai][bj][m][1];
;                     const u32x4 yv = *(const u32x4*)(Y + row * ldy + col0 + bj * HALF);
;                     u32x4 w;
;                     w.x = cvt_pk_bf16(ep_lo(yv.x) * ep_sigmoid(v0[0]), ep_hi(yv.x) * ep_sigmoid(v0[1]));
;                     w.y = cvt_pk_bf16(ep_lo(yv.y) * ep_sigmoid(v0[2]), ep_hi(yv.y) * ep_sigmoid(v0[3]));
;                     w.z = cvt_pk_bf16(ep_lo(yv.z) * ep_sigmoid(v1[0]), ep_hi(yv.z) * ep_sigmoid(v1[1]));
;                     w.w = cvt_pk_bf16(ep_lo(yv.w) * ep_sigmoid(v1[2]), ep_hi(yv.w) * ep_sigmoid(v1[3]));
.LBB0_1639:
	v_lshl_add_u32 v142, s58, 8, v144
	v_lshl_or_b32 v140, s36, 8, v146
	v_ashrrev_i32_e32 v143, 31, v142
	v_ashrrev_i32_e32 v141, 31, v140
	v_lshlrev_b64 v[148:149], 11, v[142:143]
	v_lshl_add_u64 v[148:149], s[42:43], 0, v[148:149]
	v_lshlrev_b64 v[140:141], 1, v[140:141]
	v_lshl_add_u64 v[152:153], v[148:149], 0, v[140:141]
	v_mov_b64_e32 v[236:237], v[152:153]
	global_load_dwordx4 v[156:159], v[236:237], off
	global_load_dwordx4 v[160:163], v[236:237], off offset:256
	s_mov_b64 s[100:101], 0x8000
	v_lshl_add_u64 v[236:237], v[236:237], 0, s[100:101]
	global_load_dwordx4 v[164:167], v[236:237], off
	global_load_dwordx4 v[168:171], v[236:237], off offset:256
	v_lshl_add_u64 v[236:237], v[236:237], 0, s[100:101]
	global_load_dwordx4 v[172:175], v[236:237], off
	global_load_dwordx4 v[176:179], v[236:237], off offset:256
	v_lshl_add_u64 v[236:237], v[236:237], 0, s[100:101]
	global_load_dwordx4 v[180:183], v[236:237], off
	global_load_dwordx4 v[184:187], v[236:237], off offset:256
	s_mov_b64 s[100:101], 0x28000
	v_lshl_add_u64 v[236:237], v[236:237], 0, s[100:101]
	global_load_dwordx4 v[188:191], v[236:237], off
	global_load_dwordx4 v[192:195], v[236:237], off offset:256
	s_mov_b64 s[100:101], 0x8000
	v_lshl_add_u64 v[236:237], v[236:237], 0, s[100:101]
	global_load_dwordx4 v[196:199], v[236:237], off
	global_load_dwordx4 v[200:203], v[236:237], off offset:256
	v_lshl_add_u64 v[236:237], v[236:237], 0, s[100:101]
	global_load_dwordx4 v[204:207], v[236:237], off
	global_load_dwordx4 v[224:227], v[236:237], off offset:256
	v_lshl_add_u64 v[236:237], v[236:237], 0, s[100:101]
	global_load_dwordx4 v[228:231], v[236:237], off
	global_load_dwordx4 v[232:235], v[236:237], off offset:256
	v_mul_f32_e32 v126, 0xbfb8aa3b, v126
	v_mul_f32_e32 v127, 0xbfb8aa3b, v127
	v_exp_f32_e32 v126, v126
	v_exp_f32_e32 v127, v127
	v_mul_f32_e32 v122, 0xbfb8aa3b, v122
	v_mul_f32_e32 v123, 0xbfb8aa3b, v123
	v_add_f32_e32 v126, 1.0, v126
	v_add_f32_e32 v127, 1.0, v127
	v_rcp_f32_e32 v126, v126
	v_rcp_f32_e32 v127, v127
	v_exp_f32_e32 v122, v122
	v_exp_f32_e32 v123, v123
	v_mul_f32_e32 v118, 0xbfb8aa3b, v118
	v_mul_f32_e32 v119, 0xbfb8aa3b, v119
	v_add_f32_e32 v122, 1.0, v122
	v_add_f32_e32 v123, 1.0, v123
	v_rcp_f32_e32 v122, v122
	v_rcp_f32_e32 v123, v123
	v_exp_f32_e32 v118, v118
	v_exp_f32_e32 v119, v119
	v_mul_f32_e32 v114, 0xbfb8aa3b, v114
	v_mul_f32_e32 v115, 0xbfb8aa3b, v115
	v_add_f32_e32 v118, 1.0, v118
	v_add_f32_e32 v119, 1.0, v119
	v_rcp_f32_e32 v118, v118
	v_rcp_f32_e32 v119, v119
	v_exp_f32_e32 v114, v114
	v_exp_f32_e32 v115, v115
	v_mul_f32_e32 v110, 0xbfb8aa3b, v110
	v_mul_f32_e32 v111, 0xbfb8aa3b, v111
	v_add_f32_e32 v114, 1.0, v114
	v_add_f32_e32 v115, 1.0, v115
	v_rcp_f32_e32 v114, v114
	v_rcp_f32_e32 v115, v115
	v_exp_f32_e32 v110, v110
	v_exp_f32_e32 v111, v111
	v_mul_f32_e32 v106, 0xbfb8aa3b, v106
	v_mul_f32_e32 v107, 0xbfb8aa3b, v107
	v_add_f32_e32 v110, 1.0, v110
	v_add_f32_e32 v111, 1.0, v111
	v_rcp_f32_e32 v110, v110
	v_rcp_f32_e32 v111, v111
	v_exp_f32_e32 v106, v106
	v_exp_f32_e32 v107, v107
	v_mul_f32_e32 v102, 0xbfb8aa3b, v102
	v_mul_f32_e32 v103, 0xbfb8aa3b, v103
	v_add_f32_e32 v106, 1.0, v106
	v_add_f32_e32 v107, 1.0, v107
	v_rcp_f32_e32 v106, v106
	v_rcp_f32_e32 v107, v107
	v_exp_f32_e32 v102, v102
	v_exp_f32_e32 v103, v103
	v_mul_f32_e32 v98, 0xbfb8aa3b, v98
	v_mul_f32_e32 v99, 0xbfb8aa3b, v99
	v_add_f32_e32 v102, 1.0, v102
	v_add_f32_e32 v103, 1.0, v103
	v_rcp_f32_e32 v102, v102
	v_rcp_f32_e32 v103, v103
	v_exp_f32_e32 v98, v98
	v_exp_f32_e32 v99, v99
	v_mul_f32_e32 v94, 0xbfb8aa3b, v94
	v_mul_f32_e32 v95, 0xbfb8aa3b, v95
	v_add_f32_e32 v98, 1.0, v98
	v_add_f32_e32 v99, 1.0, v99
	v_rcp_f32_e32 v98, v98
	v_rcp_f32_e32 v99, v99
	v_exp_f32_e32 v94, v94
	v_exp_f32_e32 v95, v95
	v_mul_f32_e32 v90, 0xbfb8aa3b, v90
	v_mul_f32_e32 v91, 0xbfb8aa3b, v91
	v_add_f32_e32 v94, 1.0, v94
	v_add_f32_e32 v95, 1.0, v95
	v_rcp_f32_e32 v94, v94
	v_rcp_f32_e32 v95, v95
	v_exp_f32_e32 v90, v90
	v_exp_f32_e32 v91, v91
	v_mul_f32_e32 v86, 0xbfb8aa3b, v86
	v_mul_f32_e32 v87, 0xbfb8aa3b, v87
	v_add_f32_e32 v90, 1.0, v90
	s_waitcnt vmcnt(15)
	v_mov_b64_e32 v[148:149], v[156:157]
	v_mov_b64_e32 v[150:151], v[158:159]
	v_lshlrev_b32_e32 v154, 16, v148
	v_and_b32_e32 v155, 0xffff0000, v148
	v_pk_mul_f32 v[126:127], v[126:127], v[154:155]
	v_lshlrev_b32_e32 v148, 16, v149
	v_cvt_pk_bf16_f32 v126, v126, v127
	v_mul_f32_e32 v127, 0xbfb8aa3b, v128
	v_exp_f32_e32 v127, v127
	v_and_b32_e32 v149, 0xffff0000, v149
	v_add_f32_e32 v91, 1.0, v91
	v_rcp_f32_e32 v90, v90
	v_add_f32_e32 v127, 1.0, v127
	v_rcp_f32_e32 v128, v127
	v_mul_f32_e32 v127, 0xbfb8aa3b, v129
	v_exp_f32_e32 v127, v127
	v_rcp_f32_e32 v91, v91
	v_exp_f32_e32 v86, v86
	v_exp_f32_e32 v87, v87
	v_add_f32_e32 v127, 1.0, v127
	v_rcp_f32_e32 v129, v127
	v_add_f32_e32 v86, 1.0, v86
	v_add_f32_e32 v87, 1.0, v87
	v_rcp_f32_e32 v86, v86
	v_pk_mul_f32 v[128:129], v[128:129], v[148:149]
	v_rcp_f32_e32 v87, v87
	v_cvt_pk_bf16_f32 v127, v128, v129
	v_lshlrev_b32_e32 v128, 16, v150
	v_and_b32_e32 v129, 0xffff0000, v150
	v_pk_mul_f32 v[122:123], v[122:123], v[128:129]
	v_mul_f32_e32 v82, 0xbfb8aa3b, v82
	v_cvt_pk_bf16_f32 v128, v122, v123
	v_mul_f32_e32 v122, 0xbfb8aa3b, v124
	v_mul_f32_e32 v123, 0xbfb8aa3b, v125
	v_exp_f32_e32 v122, v122
	v_exp_f32_e32 v123, v123
	v_lshlrev_b32_e32 v124, 16, v151
	v_and_b32_e32 v125, 0xffff0000, v151
	v_add_f32_e32 v122, 1.0, v122
	v_add_f32_e32 v123, 1.0, v123
	v_rcp_f32_e32 v122, v122
	v_rcp_f32_e32 v123, v123
	v_mul_f32_e32 v83, 0xbfb8aa3b, v83
	v_exp_f32_e32 v82, v82
	v_exp_f32_e32 v83, v83
	v_pk_mul_f32 v[122:123], v[122:123], v[124:125]
	v_mul_f32_e32 v78, 0xbfb8aa3b, v78
; __device__ __forceinline__ unsigned cvt_pk_bf16(float lo, float hi) { const pg8_f32x2 v = {lo, hi}; const pg8_bf16x2 b = __builtin_convertvector(v, pg8_bf16x2); return __builtin_bit_cast(unsigned, b); }
; __device__ __forceinline__ float ep_sigmoid(float x) { return __builtin_amdgcn_rcpf(1.0f + __expf(-x)); }
; __device__ __forceinline__ float ep_lo(unsigned w) { return __uint_as_float(w << 16); }
; __device__ __forceinline__ float ep_hi(unsigned w) { return __uint_as_float(w & 0xffff0000u); }
;     __device__ __forceinline__ void operator()(const f32x4 (&acc)[2][2][4][2], const Unit& u, int wr, int wc, int fr, int fq) const {
;     ...
;             for (int m = 0; m < 4; ++m) { const size_t row = (size_t)(row0 + ai * HALF + m * 16);
; #pragma unroll
;                 for (int bj = 0; bj < 2; ++bj) { const f32x4 v0 = acc[ai][bj][m][0], v1 = acc[ai][bj][m][1];
;                     const u32x4 yv = *(const u32x4*)(Y + row * ldy + col0 + bj * HALF);
;                     u32x4 w;
;                     w.x = cvt_pk_bf16(ep_lo(yv.x) * ep_sigmoid(v0[0]), ep_hi(yv.x) * ep_sigmoid(v0[1]));
;                     w.y = cvt_pk_bf16(ep_lo(yv.y) * ep_sigmoid(v0[2]), ep_hi(yv.y) * ep_sigmoid(v0[3]));
;                     w.z = cvt_pk_bf16(ep_lo(yv.z) * ep_sigmoid(v1[0]), ep_hi(yv.z) * ep_sigmoid(v1[1]));
;                     w.w = cvt_pk_bf16(ep_lo(yv.w) * ep_sigmoid(v1[2]), ep_hi(yv.w) * ep_sigmoid(v1[3]));
;                     *(u32x4*)(O + row * ldo + ocol0 + col0 + bj * HALF) = w; } }
	v_cvt_pk_bf16_f32 v129, v122, v123
	v_lshlrev_b64 v[122:123], 12, v[142:143]
	v_lshl_add_u64 v[122:123], s[46:47], 0, v[122:123]
	v_lshl_add_u64 v[148:149], v[122:123], 0, v[140:141]
	v_add_f32_e32 v82, 1.0, v82
	global_store_dwordx4 v[148:149], v[126:129], off offset:2048
	v_add_f32_e32 v83, 1.0, v83
	v_rcp_f32_e32 v82, v82
	v_rcp_f32_e32 v83, v83
	v_mul_f32_e32 v79, 0xbfb8aa3b, v79
	v_exp_f32_e32 v78, v78
	v_exp_f32_e32 v79, v79
	v_mul_f32_e32 v74, 0xbfb8aa3b, v74
	v_mul_f32_e32 v75, 0xbfb8aa3b, v75
	v_add_f32_e32 v78, 1.0, v78
	v_add_f32_e32 v79, 1.0, v79
	v_rcp_f32_e32 v78, v78
	v_rcp_f32_e32 v79, v79
	v_exp_f32_e32 v74, v74
	v_exp_f32_e32 v75, v75
	v_mul_f32_e32 v70, 0xbfb8aa3b, v70
	v_mul_f32_e32 v71, 0xbfb8aa3b, v71
	v_add_f32_e32 v74, 1.0, v74
	v_add_f32_e32 v75, 1.0, v75
	v_rcp_f32_e32 v74, v74
	v_rcp_f32_e32 v75, v75
	v_exp_f32_e32 v70, v70
	v_exp_f32_e32 v71, v71
	v_mul_f32_e32 v66, 0xbfb8aa3b, v66
	v_mul_f32_e32 v67, 0xbfb8aa3b, v67
	v_add_f32_e32 v70, 1.0, v70
	v_add_f32_e32 v71, 1.0, v71
	v_rcp_f32_e32 v70, v70
	v_rcp_f32_e32 v71, v71
	v_exp_f32_e32 v66, v66
	v_exp_f32_e32 v67, v67
	v_mul_f32_e32 v62, 0xbfb8aa3b, v62
	v_mul_f32_e32 v63, 0xbfb8aa3b, v63
	v_add_f32_e32 v66, 1.0, v66
	v_add_f32_e32 v67, 1.0, v67
	v_rcp_f32_e32 v66, v66
	v_rcp_f32_e32 v67, v67
	v_exp_f32_e32 v62, v62
	v_exp_f32_e32 v63, v63
	v_mul_f32_e32 v58, 0xbfb8aa3b, v58
	v_mul_f32_e32 v59, 0xbfb8aa3b, v59
	v_add_f32_e32 v62, 1.0, v62
	v_add_f32_e32 v63, 1.0, v63
	v_rcp_f32_e32 v62, v62
	v_rcp_f32_e32 v63, v63
	v_exp_f32_e32 v58, v58
	v_exp_f32_e32 v59, v59
	v_mul_f32_e32 v54, 0xbfb8aa3b, v54
	v_mul_f32_e32 v55, 0xbfb8aa3b, v55
	v_add_f32_e32 v58, 1.0, v58
	v_add_f32_e32 v59, 1.0, v59
	v_rcp_f32_e32 v58, v58
	v_rcp_f32_e32 v59, v59
	v_exp_f32_e32 v54, v54
	v_exp_f32_e32 v55, v55
	v_mul_f32_e32 v50, 0xbfb8aa3b, v50
	v_mul_f32_e32 v51, 0xbfb8aa3b, v51
	v_add_f32_e32 v54, 1.0, v54
	v_add_f32_e32 v55, 1.0, v55
	v_rcp_f32_e32 v54, v54
	v_rcp_f32_e32 v55, v55
	v_exp_f32_e32 v50, v50
	v_exp_f32_e32 v51, v51
	v_mul_f32_e32 v46, 0xbfb8aa3b, v46
	v_mul_f32_e32 v47, 0xbfb8aa3b, v47
	v_add_f32_e32 v50, 1.0, v50
	v_add_f32_e32 v51, 1.0, v51
	v_rcp_f32_e32 v50, v50
	v_rcp_f32_e32 v51, v51
	v_exp_f32_e32 v46, v46
	v_exp_f32_e32 v47, v47
	v_mul_f32_e32 v42, 0xbfb8aa3b, v42
	v_mul_f32_e32 v43, 0xbfb8aa3b, v43
	v_add_f32_e32 v46, 1.0, v46
	v_add_f32_e32 v47, 1.0, v47
	v_rcp_f32_e32 v46, v46
	v_rcp_f32_e32 v47, v47
	v_exp_f32_e32 v42, v42
	s_waitcnt vmcnt(15)
	v_mov_b64_e32 v[122:123], v[160:161]
	v_mov_b64_e32 v[124:125], v[162:163]
	v_lshlrev_b32_e32 v126, 16, v122
	v_and_b32_e32 v127, 0xffff0000, v122
	v_pk_mul_f32 v[118:119], v[118:119], v[126:127]
	v_lshlrev_b32_e32 v122, 16, v123
	v_cvt_pk_bf16_f32 v118, v118, v119
	v_mul_f32_e32 v119, 0xbfb8aa3b, v120
	v_exp_f32_e32 v119, v119
	v_and_b32_e32 v123, 0xffff0000, v123
	v_exp_f32_e32 v43, v43
	v_add_f32_e32 v42, 1.0, v42
	v_add_f32_e32 v119, 1.0, v119
	v_rcp_f32_e32 v120, v119
	v_mul_f32_e32 v119, 0xbfb8aa3b, v121
	v_exp_f32_e32 v119, v119
	v_add_f32_e32 v43, 1.0, v43
	v_rcp_f32_e32 v42, v42
	v_rcp_f32_e32 v43, v43
	v_add_f32_e32 v119, 1.0, v119
	v_rcp_f32_e32 v121, v119
	v_mul_f32_e32 v38, 0xbfb8aa3b, v38
	v_mul_f32_e32 v39, 0xbfb8aa3b, v39
	v_exp_f32_e32 v38, v38
	v_pk_mul_f32 v[120:121], v[120:121], v[122:123]
	v_exp_f32_e32 v39, v39
	v_cvt_pk_bf16_f32 v119, v120, v121
	v_lshlrev_b32_e32 v120, 16, v124
	v_and_b32_e32 v121, 0xffff0000, v124
	v_pk_mul_f32 v[114:115], v[114:115], v[120:121]
	v_add_f32_e32 v38, 1.0, v38
	v_cvt_pk_bf16_f32 v120, v114, v115
	v_mul_f32_e32 v114, 0xbfb8aa3b, v116
	v_mul_f32_e32 v115, 0xbfb8aa3b, v117
	v_exp_f32_e32 v114, v114
	v_exp_f32_e32 v115, v115
	v_lshlrev_b32_e32 v116, 16, v125
	v_and_b32_e32 v117, 0xffff0000, v125
	v_add_f32_e32 v114, 1.0, v114
	v_add_f32_e32 v115, 1.0, v115
	v_rcp_f32_e32 v114, v114
	v_rcp_f32_e32 v115, v115
	v_add_f32_e32 v39, 1.0, v39
	v_rcp_f32_e32 v38, v38
	v_rcp_f32_e32 v39, v39
	v_pk_mul_f32 v[114:115], v[114:115], v[116:117]
	v_mul_f32_e32 v34, 0xbfb8aa3b, v34
	v_cvt_pk_bf16_f32 v121, v114, v115
	global_store_dwordx4 v[148:149], v[118:121], off offset:2304
	v_mul_f32_e32 v35, 0xbfb8aa3b, v35
	v_exp_f32_e32 v34, v34
	v_or_b32_e32 v118, 16, v142
	v_ashrrev_i32_e32 v119, 31, v118
	v_lshlrev_b64 v[114:115], 11, v[118:119]
	v_lshl_add_u64 v[114:115], s[42:43], 0, v[114:115]
	v_lshl_add_u64 v[120:121], v[114:115], 0, v[140:141]
	v_exp_f32_e32 v35, v35
	v_add_f32_e32 v34, 1.0, v34
	v_rcp_f32_e32 v34, v34
	v_mul_f32_e32 v30, 0xbfb8aa3b, v30
	v_add_f32_e32 v35, 1.0, v35
	v_rcp_f32_e32 v35, v35
	v_mul_f32_e32 v31, 0xbfb8aa3b, v31
	v_exp_f32_e32 v30, v30
	v_exp_f32_e32 v31, v31
	v_mul_f32_e32 v26, 0xbfb8aa3b, v26
	v_mul_f32_e32 v27, 0xbfb8aa3b, v27
	v_add_f32_e32 v30, 1.0, v30
	v_add_f32_e32 v31, 1.0, v31
	v_rcp_f32_e32 v30, v30
	v_rcp_f32_e32 v31, v31
	v_exp_f32_e32 v26, v26
	v_exp_f32_e32 v27, v27
	v_mul_f32_e32 v22, 0xbfb8aa3b, v22
	v_mul_f32_e32 v23, 0xbfb8aa3b, v23
	v_add_f32_e32 v26, 1.0, v26
	v_add_f32_e32 v27, 1.0, v27
	v_rcp_f32_e32 v26, v26
	v_rcp_f32_e32 v27, v27
	v_exp_f32_e32 v22, v22
	v_exp_f32_e32 v23, v23
	v_mul_f32_e32 v18, 0xbfb8aa3b, v18
	v_mul_f32_e32 v19, 0xbfb8aa3b, v19
	v_add_f32_e32 v22, 1.0, v22
	v_add_f32_e32 v23, 1.0, v23
	v_rcp_f32_e32 v22, v22
	v_rcp_f32_e32 v23, v23
	v_exp_f32_e32 v18, v18
	v_exp_f32_e32 v19, v19
	v_mul_f32_e32 v14, 0xbfb8aa3b, v14
	v_mul_f32_e32 v15, 0xbfb8aa3b, v15
	v_add_f32_e32 v18, 1.0, v18
	v_add_f32_e32 v19, 1.0, v19
	v_rcp_f32_e32 v18, v18
	v_rcp_f32_e32 v19, v19
	v_exp_f32_e32 v14, v14
	v_exp_f32_e32 v15, v15
	v_mul_f32_e32 v10, 0xbfb8aa3b, v10
	v_mul_f32_e32 v11, 0xbfb8aa3b, v11
	v_add_f32_e32 v14, 1.0, v14
	v_add_f32_e32 v15, 1.0, v15
	v_rcp_f32_e32 v14, v14
	v_rcp_f32_e32 v15, v15
	v_exp_f32_e32 v10, v10
	v_exp_f32_e32 v11, v11
	v_mul_f32_e32 v6, 0xbfb8aa3b, v6
	v_mul_f32_e32 v7, 0xbfb8aa3b, v7
	v_add_f32_e32 v10, 1.0, v10
	v_add_f32_e32 v11, 1.0, v11
	v_rcp_f32_e32 v10, v10
	v_rcp_f32_e32 v11, v11
	v_exp_f32_e32 v6, v6
	v_exp_f32_e32 v7, v7
	v_mul_f32_e32 v2, 0xbfb8aa3b, v2
	v_mul_f32_e32 v3, 0xbfb8aa3b, v3
	v_add_f32_e32 v6, 1.0, v6
	v_add_f32_e32 v7, 1.0, v7
	v_rcp_f32_e32 v6, v6
	v_rcp_f32_e32 v7, v7
	v_exp_f32_e32 v2, v2
	v_exp_f32_e32 v3, v3
	s_mov_b64 s[0:1], -1
	s_andn2_b64 vcc, exec, s[38:39]
	v_add_f32_e32 v2, 1.0, v2
	v_add_f32_e32 v3, 1.0, v3
	v_rcp_f32_e32 v2, v2
	v_rcp_f32_e32 v3, v3
	s_waitcnt vmcnt(15)
; __device__ __forceinline__ unsigned cvt_pk_bf16(float lo, float hi) { const pg8_f32x2 v = {lo, hi}; const pg8_bf16x2 b = __builtin_convertvector(v, pg8_bf16x2); return __builtin_bit_cast(unsigned, b); }
; __device__ __forceinline__ float ep_sigmoid(float x) { return __builtin_amdgcn_rcpf(1.0f + __expf(-x)); }
; __device__ __forceinline__ float ep_lo(unsigned w) { return __uint_as_float(w << 16); }
; __device__ __forceinline__ float ep_hi(unsigned w) { return __uint_as_float(w & 0xffff0000u); }
;     __device__ __forceinline__ void operator()(const f32x4 (&acc)[2][2][4][2], const Unit& u, int wr, int wc, int fr, int fq) const {
;     ...
;             for (int m = 0; m < 4; ++m) { const size_t row = (size_t)(row0 + ai * HALF + m * 16);
; #pragma unroll
;                 for (int bj = 0; bj < 2; ++bj) { const f32x4 v0 = acc[ai][bj][m][0], v1 = acc[ai][bj][m][1];
;                     const u32x4 yv = *(const u32x4*)(Y + row * ldy + col0 + bj * HALF);
;                     u32x4 w;
;                     w.x = cvt_pk_bf16(ep_lo(yv.x) * ep_sigmoid(v0[0]), ep_hi(yv.x) * ep_sigmoid(v0[1]));
;                     w.y = cvt_pk_bf16(ep_lo(yv.y) * ep_sigmoid(v0[2]), ep_hi(yv.y) * ep_sigmoid(v0[3]));
;                     w.z = cvt_pk_bf16(ep_lo(yv.z) * ep_sigmoid(v1[0]), ep_hi(yv.z) * ep_sigmoid(v1[1]));
;                     w.w = cvt_pk_bf16(ep_lo(yv.w) * ep_sigmoid(v1[2]), ep_hi(yv.w) * ep_sigmoid(v1[3]));
;                     *(u32x4*)(O + row * ldo + ocol0 + col0 + bj * HALF) = w; } }
	v_mov_b64_e32 v[114:115], v[164:165]
	v_mov_b64_e32 v[116:117], v[166:167]
	v_lshlrev_b32_e32 v122, 16, v114
	v_and_b32_e32 v123, 0xffff0000, v114
	v_pk_mul_f32 v[110:111], v[110:111], v[122:123]
	v_lshlrev_b32_e32 v114, 16, v115
	v_cvt_pk_bf16_f32 v110, v110, v111
	v_mul_f32_e32 v111, 0xbfb8aa3b, v112
	v_exp_f32_e32 v111, v111
	v_and_b32_e32 v115, 0xffff0000, v115
	v_add_f32_e32 v111, 1.0, v111
	v_rcp_f32_e32 v112, v111
	v_mul_f32_e32 v111, 0xbfb8aa3b, v113
	v_exp_f32_e32 v111, v111
	s_nop 0
	v_add_f32_e32 v111, 1.0, v111
	v_rcp_f32_e32 v113, v111
	s_nop 0
	v_pk_mul_f32 v[112:113], v[112:113], v[114:115]
	s_nop 0
	v_cvt_pk_bf16_f32 v111, v112, v113
	v_lshlrev_b32_e32 v112, 16, v116
	v_and_b32_e32 v113, 0xffff0000, v116
	v_pk_mul_f32 v[106:107], v[106:107], v[112:113]
	s_nop 0
	v_cvt_pk_bf16_f32 v112, v106, v107
	v_mul_f32_e32 v106, 0xbfb8aa3b, v108
	v_mul_f32_e32 v107, 0xbfb8aa3b, v109
	v_exp_f32_e32 v106, v106
	v_exp_f32_e32 v107, v107
	v_lshlrev_b32_e32 v108, 16, v117
	v_and_b32_e32 v109, 0xffff0000, v117
	v_add_f32_e32 v106, 1.0, v106
	v_add_f32_e32 v107, 1.0, v107
	v_rcp_f32_e32 v106, v106
	v_rcp_f32_e32 v107, v107
	s_nop 0
	v_pk_mul_f32 v[106:107], v[106:107], v[108:109]
	s_nop 0
	v_cvt_pk_bf16_f32 v113, v106, v107
	v_lshlrev_b64 v[106:107], 12, v[118:119]
	v_lshl_add_u64 v[106:107], s[46:47], 0, v[106:107]
	v_lshl_add_u64 v[114:115], v[106:107], 0, v[140:141]
	s_nop 0
	global_store_dwordx4 v[114:115], v[110:113], off offset:2048
	s_waitcnt vmcnt(15)
	v_mov_b64_e32 v[106:107], v[168:169]
	v_mov_b64_e32 v[108:109], v[170:171]
	s_nop 0
	v_lshlrev_b32_e32 v110, 16, v106
	v_and_b32_e32 v111, 0xffff0000, v106
	v_pk_mul_f32 v[102:103], v[102:103], v[110:111]
	v_lshlrev_b32_e32 v106, 16, v107
	v_cvt_pk_bf16_f32 v102, v102, v103
	v_mul_f32_e32 v103, 0xbfb8aa3b, v104
	v_exp_f32_e32 v103, v103
	v_and_b32_e32 v107, 0xffff0000, v107
	v_add_f32_e32 v103, 1.0, v103
	v_rcp_f32_e32 v104, v103
	v_mul_f32_e32 v103, 0xbfb8aa3b, v105
	v_exp_f32_e32 v103, v103
	s_nop 0
	v_add_f32_e32 v103, 1.0, v103
	v_rcp_f32_e32 v105, v103
	s_nop 0
	v_pk_mul_f32 v[104:105], v[104:105], v[106:107]
	s_nop 0
	v_cvt_pk_bf16_f32 v103, v104, v105
	v_lshlrev_b32_e32 v104, 16, v108
	v_and_b32_e32 v105, 0xffff0000, v108
	v_pk_mul_f32 v[98:99], v[98:99], v[104:105]
	s_nop 0
	v_cvt_pk_bf16_f32 v104, v98, v99
	v_mul_f32_e32 v98, 0xbfb8aa3b, v100
	v_mul_f32_e32 v99, 0xbfb8aa3b, v101
	v_exp_f32_e32 v98, v98
	v_exp_f32_e32 v99, v99
	v_lshlrev_b32_e32 v100, 16, v109
	v_and_b32_e32 v101, 0xffff0000, v109
	v_add_f32_e32 v98, 1.0, v98
	v_add_f32_e32 v99, 1.0, v99
	v_rcp_f32_e32 v98, v98
	v_rcp_f32_e32 v99, v99
	s_nop 0
	v_pk_mul_f32 v[98:99], v[98:99], v[100:101]
	s_nop 0
	v_cvt_pk_bf16_f32 v105, v98, v99
	v_or_b32_e32 v98, 32, v142
	v_ashrrev_i32_e32 v99, 31, v98
	v_lshlrev_b64 v[100:101], 11, v[98:99]
	v_lshl_add_u64 v[100:101], s[42:43], 0, v[100:101]
	v_lshl_add_u64 v[100:101], v[100:101], 0, v[140:141]
	global_store_dwordx4 v[114:115], v[102:105], off offset:2304
	s_waitcnt vmcnt(15)
	v_mov_b64_e32 v[102:103], v[172:173]
	v_mov_b64_e32 v[104:105], v[174:175]
	v_lshlrev_b32_e32 v106, 16, v102
	v_and_b32_e32 v107, 0xffff0000, v102
	v_pk_mul_f32 v[94:95], v[94:95], v[106:107]
	v_lshlrev_b32_e32 v102, 16, v103
	v_cvt_pk_bf16_f32 v94, v94, v95
	v_mul_f32_e32 v95, 0xbfb8aa3b, v96
	v_exp_f32_e32 v95, v95
	v_and_b32_e32 v103, 0xffff0000, v103
	v_add_f32_e32 v95, 1.0, v95
	v_rcp_f32_e32 v96, v95
	v_mul_f32_e32 v95, 0xbfb8aa3b, v97
	v_exp_f32_e32 v95, v95
	s_nop 0
	v_add_f32_e32 v95, 1.0, v95
	v_rcp_f32_e32 v97, v95
	s_nop 0
	v_pk_mul_f32 v[96:97], v[96:97], v[102:103]
	s_nop 0
	v_cvt_pk_bf16_f32 v95, v96, v97
	v_lshlrev_b32_e32 v96, 16, v104
	v_and_b32_e32 v97, 0xffff0000, v104
	v_pk_mul_f32 v[90:91], v[90:91], v[96:97]
	s_nop 0
	v_cvt_pk_bf16_f32 v96, v90, v91
	v_mul_f32_e32 v90, 0xbfb8aa3b, v92
	v_mul_f32_e32 v91, 0xbfb8aa3b, v93
	v_exp_f32_e32 v90, v90
	v_exp_f32_e32 v91, v91
	v_lshlrev_b32_e32 v92, 16, v105
	v_and_b32_e32 v93, 0xffff0000, v105
	v_add_f32_e32 v90, 1.0, v90
	v_add_f32_e32 v91, 1.0, v91
	v_rcp_f32_e32 v90, v90
	v_rcp_f32_e32 v91, v91
	s_nop 0
	v_pk_mul_f32 v[90:91], v[90:91], v[92:93]
	s_nop 0
	v_cvt_pk_bf16_f32 v97, v90, v91
	v_lshlrev_b64 v[90:91], 12, v[98:99]
	v_lshl_add_u64 v[90:91], s[46:47], 0, v[90:91]
	v_lshl_add_u64 v[90:91], v[90:91], 0, v[140:141]
	global_store_dwordx4 v[90:91], v[94:97], off offset:2048
	s_waitcnt vmcnt(15)
	v_mov_b64_e32 v[92:93], v[176:177]
	v_mov_b64_e32 v[94:95], v[178:179]
	v_lshlrev_b32_e32 v96, 16, v92
	v_and_b32_e32 v97, 0xffff0000, v92
	v_pk_mul_f32 v[86:87], v[86:87], v[96:97]
	v_lshlrev_b32_e32 v92, 16, v93
	v_cvt_pk_bf16_f32 v86, v86, v87
	v_mul_f32_e32 v87, 0xbfb8aa3b, v88
	v_exp_f32_e32 v87, v87
	v_and_b32_e32 v93, 0xffff0000, v93
	v_add_f32_e32 v87, 1.0, v87
	v_rcp_f32_e32 v88, v87
	v_mul_f32_e32 v87, 0xbfb8aa3b, v89
	v_exp_f32_e32 v87, v87
	s_nop 0
	v_add_f32_e32 v87, 1.0, v87
	v_rcp_f32_e32 v89, v87
	s_nop 0
	v_pk_mul_f32 v[88:89], v[88:89], v[92:93]
	s_nop 0
	v_cvt_pk_bf16_f32 v87, v88, v89
	v_lshlrev_b32_e32 v88, 16, v94
	v_and_b32_e32 v89, 0xffff0000, v94
	v_pk_mul_f32 v[82:83], v[82:83], v[88:89]
	s_nop 0
	v_cvt_pk_bf16_f32 v88, v82, v83
	v_mul_f32_e32 v82, 0xbfb8aa3b, v84
	v_mul_f32_e32 v83, 0xbfb8aa3b, v85
	v_exp_f32_e32 v82, v82
	v_exp_f32_e32 v83, v83
	v_lshlrev_b32_e32 v84, 16, v95
	v_and_b32_e32 v85, 0xffff0000, v95
	v_add_f32_e32 v82, 1.0, v82
	v_add_f32_e32 v83, 1.0, v83
	v_rcp_f32_e32 v82, v82
	v_rcp_f32_e32 v83, v83
	s_nop 0
	v_pk_mul_f32 v[82:83], v[82:83], v[84:85]
	s_nop 0
	v_cvt_pk_bf16_f32 v89, v82, v83
	global_store_dwordx4 v[90:91], v[86:89], off offset:2304
	s_nop 1
	v_or_b32_e32 v88, 48, v142
	v_ashrrev_i32_e32 v89, 31, v88
	v_lshlrev_b64 v[82:83], 11, v[88:89]
	v_lshl_add_u64 v[82:83], s[42:43], 0, v[82:83]
	v_lshl_add_u64 v[86:87], v[82:83], 0, v[140:141]
	s_waitcnt vmcnt(15)
; __device__ __forceinline__ unsigned cvt_pk_bf16(float lo, float hi) { const pg8_f32x2 v = {lo, hi}; const pg8_bf16x2 b = __builtin_convertvector(v, pg8_bf16x2); return __builtin_bit_cast(unsigned, b); }
; __device__ __forceinline__ float ep_sigmoid(float x) { return __builtin_amdgcn_rcpf(1.0f + __expf(-x)); }
; __device__ __forceinline__ float ep_lo(unsigned w) { return __uint_as_float(w << 16); }
; __device__ __forceinline__ float ep_hi(unsigned w) { return __uint_as_float(w & 0xffff0000u); }
;     __device__ __forceinline__ void operator()(const f32x4 (&acc)[2][2][4][2], const Unit& u, int wr, int wc, int fr, int fq) const {
;     ...
;             for (int m = 0; m < 4; ++m) { const size_t row = (size_t)(row0 + ai * HALF + m * 16);
; #pragma unroll
;                 for (int bj = 0; bj < 2; ++bj) { const f32x4 v0 = acc[ai][bj][m][0], v1 = acc[ai][bj][m][1];
;                     const u32x4 yv = *(const u32x4*)(Y + row * ldy + col0 + bj * HALF);
;                     u32x4 w;
;                     w.x = cvt_pk_bf16(ep_lo(yv.x) * ep_sigmoid(v0[0]), ep_hi(yv.x) * ep_sigmoid(v0[1]));
;                     w.y = cvt_pk_bf16(ep_lo(yv.y) * ep_sigmoid(v0[2]), ep_hi(yv.y) * ep_sigmoid(v0[3]));
;                     w.z = cvt_pk_bf16(ep_lo(yv.z) * ep_sigmoid(v1[0]), ep_hi(yv.z) * ep_sigmoid(v1[1]));
;                     w.w = cvt_pk_bf16(ep_lo(yv.w) * ep_sigmoid(v1[2]), ep_hi(yv.w) * ep_sigmoid(v1[3]));
;                     *(u32x4*)(O + row * ldo + ocol0 + col0 + bj * HALF) = w; } }
	v_mov_b64_e32 v[82:83], v[180:181]
	v_mov_b64_e32 v[84:85], v[182:183]
	v_lshlrev_b32_e32 v90, 16, v82
	v_and_b32_e32 v91, 0xffff0000, v82
	v_pk_mul_f32 v[78:79], v[78:79], v[90:91]
	v_lshlrev_b32_e32 v82, 16, v83
	v_cvt_pk_bf16_f32 v78, v78, v79
	v_mul_f32_e32 v79, 0xbfb8aa3b, v80
	v_exp_f32_e32 v79, v79
	v_and_b32_e32 v83, 0xffff0000, v83
	v_add_f32_e32 v79, 1.0, v79
	v_rcp_f32_e32 v80, v79
	v_mul_f32_e32 v79, 0xbfb8aa3b, v81
	v_exp_f32_e32 v79, v79
	s_nop 0
	v_add_f32_e32 v79, 1.0, v79
	v_rcp_f32_e32 v81, v79
	s_nop 0
	v_pk_mul_f32 v[80:81], v[80:81], v[82:83]
	s_nop 0
	v_cvt_pk_bf16_f32 v79, v80, v81
	v_lshlrev_b32_e32 v80, 16, v84
	v_and_b32_e32 v81, 0xffff0000, v84
	v_pk_mul_f32 v[74:75], v[74:75], v[80:81]
	s_nop 0
	v_cvt_pk_bf16_f32 v80, v74, v75
	v_mul_f32_e32 v74, 0xbfb8aa3b, v76
	v_mul_f32_e32 v75, 0xbfb8aa3b, v77
	v_exp_f32_e32 v74, v74
	v_exp_f32_e32 v75, v75
	v_lshlrev_b32_e32 v76, 16, v85
	v_and_b32_e32 v77, 0xffff0000, v85
	v_add_f32_e32 v74, 1.0, v74
	v_add_f32_e32 v75, 1.0, v75
	v_rcp_f32_e32 v74, v74
	v_rcp_f32_e32 v75, v75
	s_nop 0
	v_pk_mul_f32 v[74:75], v[74:75], v[76:77]
	s_nop 0
	v_cvt_pk_bf16_f32 v81, v74, v75
	v_lshlrev_b64 v[74:75], 12, v[88:89]
	v_lshl_add_u64 v[74:75], s[46:47], 0, v[74:75]
	v_lshl_add_u64 v[82:83], v[74:75], 0, v[140:141]
	s_nop 0
	global_store_dwordx4 v[82:83], v[78:81], off offset:2048
	s_waitcnt vmcnt(15)
	v_mov_b64_e32 v[74:75], v[184:185]
	v_mov_b64_e32 v[76:77], v[186:187]
	s_nop 0
	v_lshlrev_b32_e32 v78, 16, v74
	v_and_b32_e32 v79, 0xffff0000, v74
	v_pk_mul_f32 v[70:71], v[70:71], v[78:79]
	v_lshlrev_b32_e32 v74, 16, v75
	v_cvt_pk_bf16_f32 v70, v70, v71
	v_mul_f32_e32 v71, 0xbfb8aa3b, v72
	v_exp_f32_e32 v71, v71
	v_and_b32_e32 v75, 0xffff0000, v75
	v_add_f32_e32 v71, 1.0, v71
	v_rcp_f32_e32 v72, v71
	v_mul_f32_e32 v71, 0xbfb8aa3b, v73
	v_exp_f32_e32 v71, v71
	s_nop 0
	v_add_f32_e32 v71, 1.0, v71
	v_rcp_f32_e32 v73, v71
	s_nop 0
	v_pk_mul_f32 v[72:73], v[72:73], v[74:75]
	s_nop 0
	v_cvt_pk_bf16_f32 v71, v72, v73
	v_lshlrev_b32_e32 v72, 16, v76
	v_and_b32_e32 v73, 0xffff0000, v76
	v_pk_mul_f32 v[66:67], v[66:67], v[72:73]
	s_nop 0
	v_cvt_pk_bf16_f32 v72, v66, v67
	v_mul_f32_e32 v66, 0xbfb8aa3b, v68
	v_mul_f32_e32 v67, 0xbfb8aa3b, v69
	v_exp_f32_e32 v66, v66
	v_exp_f32_e32 v67, v67
	v_lshlrev_b32_e32 v68, 16, v77
	v_and_b32_e32 v69, 0xffff0000, v77
	v_add_f32_e32 v66, 1.0, v66
	v_add_f32_e32 v67, 1.0, v67
	v_rcp_f32_e32 v66, v66
	v_rcp_f32_e32 v67, v67
	s_nop 0
	v_pk_mul_f32 v[66:67], v[66:67], v[68:69]
	v_add_u32_e32 v68, 0x80, v142
	v_ashrrev_i32_e32 v69, 31, v68
	v_cvt_pk_bf16_f32 v73, v66, v67
	v_lshlrev_b64 v[66:67], 11, v[68:69]
	v_lshl_add_u64 v[66:67], s[42:43], 0, v[66:67]
	v_lshl_add_u64 v[66:67], v[66:67], 0, v[140:141]
	global_store_dwordx4 v[82:83], v[70:73], off offset:2304
	s_waitcnt vmcnt(15)
	v_mov_b64_e32 v[70:71], v[188:189]
	v_mov_b64_e32 v[72:73], v[190:191]
	v_lshlrev_b32_e32 v74, 16, v70
	v_and_b32_e32 v75, 0xffff0000, v70
	v_pk_mul_f32 v[62:63], v[62:63], v[74:75]
	v_lshlrev_b32_e32 v70, 16, v71
	v_cvt_pk_bf16_f32 v62, v62, v63
	v_mul_f32_e32 v63, 0xbfb8aa3b, v64
	v_exp_f32_e32 v63, v63
	v_and_b32_e32 v71, 0xffff0000, v71
	v_add_f32_e32 v63, 1.0, v63
	v_rcp_f32_e32 v64, v63
	v_mul_f32_e32 v63, 0xbfb8aa3b, v65
	v_exp_f32_e32 v63, v63
	s_nop 0
	v_add_f32_e32 v63, 1.0, v63
	v_rcp_f32_e32 v65, v63
	s_nop 0
	v_pk_mul_f32 v[64:65], v[64:65], v[70:71]
	s_nop 0
	v_cvt_pk_bf16_f32 v63, v64, v65
	v_lshlrev_b32_e32 v64, 16, v72
	v_and_b32_e32 v65, 0xffff0000, v72
	v_pk_mul_f32 v[58:59], v[58:59], v[64:65]
	s_nop 0
	v_cvt_pk_bf16_f32 v64, v58, v59
	v_mul_f32_e32 v58, 0xbfb8aa3b, v60
	v_mul_f32_e32 v59, 0xbfb8aa3b, v61
	v_exp_f32_e32 v58, v58
	v_exp_f32_e32 v59, v59
	v_lshlrev_b32_e32 v60, 16, v73
	v_and_b32_e32 v61, 0xffff0000, v73
	v_add_f32_e32 v58, 1.0, v58
	v_add_f32_e32 v59, 1.0, v59
	v_rcp_f32_e32 v58, v58
	v_rcp_f32_e32 v59, v59
	s_nop 0
	v_pk_mul_f32 v[58:59], v[58:59], v[60:61]
	s_nop 0
	v_cvt_pk_bf16_f32 v65, v58, v59
	v_lshlrev_b64 v[58:59], 12, v[68:69]
	v_lshl_add_u64 v[58:59], s[46:47], 0, v[58:59]
	v_lshl_add_u64 v[58:59], v[58:59], 0, v[140:141]
	global_store_dwordx4 v[58:59], v[62:65], off offset:2048
	s_waitcnt vmcnt(15)
	v_mov_b64_e32 v[60:61], v[192:193]
	v_mov_b64_e32 v[62:63], v[194:195]
	v_lshlrev_b32_e32 v64, 16, v60
	v_and_b32_e32 v65, 0xffff0000, v60
	v_pk_mul_f32 v[54:55], v[54:55], v[64:65]
	v_lshlrev_b32_e32 v60, 16, v61
	v_cvt_pk_bf16_f32 v54, v54, v55
	v_mul_f32_e32 v55, 0xbfb8aa3b, v56
	v_exp_f32_e32 v55, v55
	v_and_b32_e32 v61, 0xffff0000, v61
	v_add_f32_e32 v55, 1.0, v55
	v_rcp_f32_e32 v56, v55
	v_mul_f32_e32 v55, 0xbfb8aa3b, v57
	v_exp_f32_e32 v55, v55
	s_nop 0
	v_add_f32_e32 v55, 1.0, v55
	v_rcp_f32_e32 v57, v55
	s_nop 0
	v_pk_mul_f32 v[56:57], v[56:57], v[60:61]
	s_nop 0
	v_cvt_pk_bf16_f32 v55, v56, v57
	v_lshlrev_b32_e32 v56, 16, v62
	v_and_b32_e32 v57, 0xffff0000, v62
	v_pk_mul_f32 v[50:51], v[50:51], v[56:57]
	s_nop 0
	v_cvt_pk_bf16_f32 v56, v50, v51
	v_mul_f32_e32 v50, 0xbfb8aa3b, v52
	v_mul_f32_e32 v51, 0xbfb8aa3b, v53
	v_exp_f32_e32 v50, v50
	v_exp_f32_e32 v51, v51
	v_lshlrev_b32_e32 v52, 16, v63
	v_and_b32_e32 v53, 0xffff0000, v63
	v_add_f32_e32 v50, 1.0, v50
	v_add_f32_e32 v51, 1.0, v51
	v_rcp_f32_e32 v50, v50
	v_rcp_f32_e32 v51, v51
	s_nop 0
	v_pk_mul_f32 v[50:51], v[50:51], v[52:53]
	s_nop 0
	v_cvt_pk_bf16_f32 v57, v50, v51
	global_store_dwordx4 v[58:59], v[54:57], off offset:2304
	s_nop 1
	v_add_u32_e32 v56, 0x90, v142
	v_ashrrev_i32_e32 v57, 31, v56
	v_lshlrev_b64 v[50:51], 11, v[56:57]
	v_lshl_add_u64 v[50:51], s[42:43], 0, v[50:51]
	v_lshl_add_u64 v[50:51], v[50:51], 0, v[140:141]
	s_waitcnt vmcnt(15)
; __device__ __forceinline__ unsigned cvt_pk_bf16(float lo, float hi) { const pg8_f32x2 v = {lo, hi}; const pg8_bf16x2 b = __builtin_convertvector(v, pg8_bf16x2); return __builtin_bit_cast(unsigned, b); }
; __device__ __forceinline__ float ep_sigmoid(float x) { return __builtin_amdgcn_rcpf(1.0f + __expf(-x)); }
; __device__ __forceinline__ float ep_lo(unsigned w) { return __uint_as_float(w << 16); }
; __device__ __forceinline__ float ep_hi(unsigned w) { return __uint_as_float(w & 0xffff0000u); }
;     __device__ __forceinline__ void operator()(const f32x4 (&acc)[2][2][4][2], const Unit& u, int wr, int wc, int fr, int fq) const {
;     ...
;             for (int m = 0; m < 4; ++m) { const size_t row = (size_t)(row0 + ai * HALF + m * 16);
; #pragma unroll
;                 for (int bj = 0; bj < 2; ++bj) { const f32x4 v0 = acc[ai][bj][m][0], v1 = acc[ai][bj][m][1];
;                     const u32x4 yv = *(const u32x4*)(Y + row * ldy + col0 + bj * HALF);
;                     u32x4 w;
;                     w.x = cvt_pk_bf16(ep_lo(yv.x) * ep_sigmoid(v0[0]), ep_hi(yv.x) * ep_sigmoid(v0[1]));
;                     w.y = cvt_pk_bf16(ep_lo(yv.y) * ep_sigmoid(v0[2]), ep_hi(yv.y) * ep_sigmoid(v0[3]));
;                     w.z = cvt_pk_bf16(ep_lo(yv.z) * ep_sigmoid(v1[0]), ep_hi(yv.z) * ep_sigmoid(v1[1]));
;                     w.w = cvt_pk_bf16(ep_lo(yv.w) * ep_sigmoid(v1[2]), ep_hi(yv.w) * ep_sigmoid(v1[3]));
;                     *(u32x4*)(O + row * ldo + ocol0 + col0 + bj * HALF) = w; } }
	v_mov_b64_e32 v[52:53], v[196:197]
	v_mov_b64_e32 v[54:55], v[198:199]
	v_lshlrev_b32_e32 v58, 16, v52
	v_and_b32_e32 v59, 0xffff0000, v52
	v_pk_mul_f32 v[46:47], v[46:47], v[58:59]
	v_lshlrev_b32_e32 v52, 16, v53
	v_cvt_pk_bf16_f32 v46, v46, v47
	v_mul_f32_e32 v47, 0xbfb8aa3b, v48
	v_exp_f32_e32 v47, v47
	v_and_b32_e32 v53, 0xffff0000, v53
	v_add_f32_e32 v47, 1.0, v47
	v_rcp_f32_e32 v48, v47
	v_mul_f32_e32 v47, 0xbfb8aa3b, v49
	v_exp_f32_e32 v47, v47
	s_nop 0
	v_add_f32_e32 v47, 1.0, v47
	v_rcp_f32_e32 v49, v47
	s_nop 0
	v_pk_mul_f32 v[48:49], v[48:49], v[52:53]
	s_nop 0
	v_cvt_pk_bf16_f32 v47, v48, v49
	v_lshlrev_b32_e32 v48, 16, v54
	v_and_b32_e32 v49, 0xffff0000, v54
	v_pk_mul_f32 v[42:43], v[42:43], v[48:49]
	s_nop 0
	v_cvt_pk_bf16_f32 v48, v42, v43
	v_mul_f32_e32 v42, 0xbfb8aa3b, v44
	v_mul_f32_e32 v43, 0xbfb8aa3b, v45
	v_exp_f32_e32 v42, v42
	v_exp_f32_e32 v43, v43
	v_lshlrev_b32_e32 v44, 16, v55
	v_and_b32_e32 v45, 0xffff0000, v55
	v_add_f32_e32 v42, 1.0, v42
	v_add_f32_e32 v43, 1.0, v43
	v_rcp_f32_e32 v42, v42
	v_rcp_f32_e32 v43, v43
	s_nop 0
	v_pk_mul_f32 v[42:43], v[42:43], v[44:45]
	s_nop 0
	v_cvt_pk_bf16_f32 v49, v42, v43
	v_lshlrev_b64 v[42:43], 12, v[56:57]
	v_lshl_add_u64 v[42:43], s[46:47], 0, v[42:43]
	v_lshl_add_u64 v[42:43], v[42:43], 0, v[140:141]
	global_store_dwordx4 v[42:43], v[46:49], off offset:2048
	s_waitcnt vmcnt(15)
	v_mov_b64_e32 v[44:45], v[200:201]
	v_mov_b64_e32 v[46:47], v[202:203]
	v_lshlrev_b32_e32 v48, 16, v44
	v_and_b32_e32 v49, 0xffff0000, v44
	v_pk_mul_f32 v[38:39], v[38:39], v[48:49]
	v_lshlrev_b32_e32 v44, 16, v45
	v_cvt_pk_bf16_f32 v38, v38, v39
	v_mul_f32_e32 v39, 0xbfb8aa3b, v40
	v_exp_f32_e32 v39, v39
	v_and_b32_e32 v45, 0xffff0000, v45
	v_add_f32_e32 v39, 1.0, v39
	v_rcp_f32_e32 v40, v39
	v_mul_f32_e32 v39, 0xbfb8aa3b, v41
	v_exp_f32_e32 v39, v39
	s_nop 0
	v_add_f32_e32 v39, 1.0, v39
	v_rcp_f32_e32 v41, v39
	s_nop 0
	v_pk_mul_f32 v[40:41], v[40:41], v[44:45]
	s_nop 0
	v_cvt_pk_bf16_f32 v39, v40, v41
	v_lshlrev_b32_e32 v40, 16, v46
	v_and_b32_e32 v41, 0xffff0000, v46
	v_pk_mul_f32 v[34:35], v[34:35], v[40:41]
	s_nop 0
	v_cvt_pk_bf16_f32 v40, v34, v35
	v_mul_f32_e32 v34, 0xbfb8aa3b, v36
	v_mul_f32_e32 v35, 0xbfb8aa3b, v37
	v_exp_f32_e32 v34, v34
	v_exp_f32_e32 v35, v35
	v_lshlrev_b32_e32 v36, 16, v47
	v_and_b32_e32 v37, 0xffff0000, v47
	v_add_f32_e32 v34, 1.0, v34
	v_add_f32_e32 v35, 1.0, v35
	v_rcp_f32_e32 v34, v34
	v_rcp_f32_e32 v35, v35
	s_nop 0
	v_pk_mul_f32 v[34:35], v[34:35], v[36:37]
	s_nop 0
	v_cvt_pk_bf16_f32 v41, v34, v35
	global_store_dwordx4 v[42:43], v[38:41], off offset:2304
	s_nop 1
	v_add_u32_e32 v40, 0xa0, v142
	v_ashrrev_i32_e32 v41, 31, v40
	v_lshlrev_b64 v[34:35], 11, v[40:41]
	v_lshl_add_u64 v[34:35], s[42:43], 0, v[34:35]
	v_lshl_add_u64 v[34:35], v[34:35], 0, v[140:141]
	s_waitcnt vmcnt(15)
	v_mov_b64_e32 v[36:37], v[204:205]
	v_mov_b64_e32 v[38:39], v[206:207]
	v_lshlrev_b32_e32 v42, 16, v36
	v_and_b32_e32 v43, 0xffff0000, v36
	v_pk_mul_f32 v[30:31], v[30:31], v[42:43]
	v_lshlrev_b32_e32 v36, 16, v37
	v_cvt_pk_bf16_f32 v30, v30, v31
	v_mul_f32_e32 v31, 0xbfb8aa3b, v32
	v_exp_f32_e32 v31, v31
	v_and_b32_e32 v37, 0xffff0000, v37
	v_add_f32_e32 v31, 1.0, v31
	v_rcp_f32_e32 v32, v31
	v_mul_f32_e32 v31, 0xbfb8aa3b, v33
	v_exp_f32_e32 v31, v31
	s_nop 0
	v_add_f32_e32 v31, 1.0, v31
	v_rcp_f32_e32 v33, v31
	s_nop 0
	v_pk_mul_f32 v[32:33], v[32:33], v[36:37]
	s_nop 0
	v_cvt_pk_bf16_f32 v31, v32, v33
	v_lshlrev_b32_e32 v32, 16, v38
	v_and_b32_e32 v33, 0xffff0000, v38
	v_pk_mul_f32 v[26:27], v[26:27], v[32:33]
	s_nop 0
	v_cvt_pk_bf16_f32 v32, v26, v27
	v_mul_f32_e32 v26, 0xbfb8aa3b, v28
	v_mul_f32_e32 v27, 0xbfb8aa3b, v29
	v_exp_f32_e32 v26, v26
	v_exp_f32_e32 v27, v27
	v_lshlrev_b32_e32 v28, 16, v39
	v_and_b32_e32 v29, 0xffff0000, v39
	v_add_f32_e32 v26, 1.0, v26
	v_add_f32_e32 v27, 1.0, v27
	v_rcp_f32_e32 v26, v26
	v_rcp_f32_e32 v27, v27
	s_nop 0
	v_pk_mul_f32 v[26:27], v[26:27], v[28:29]
	s_nop 0
	v_cvt_pk_bf16_f32 v33, v26, v27
	v_lshlrev_b64 v[26:27], 12, v[40:41]
	v_lshl_add_u64 v[26:27], s[46:47], 0, v[26:27]
	v_lshl_add_u64 v[26:27], v[26:27], 0, v[140:141]
	global_store_dwordx4 v[26:27], v[30:33], off offset:2048
	s_waitcnt vmcnt(15)
; __device__ __forceinline__ unsigned cvt_pk_bf16(float lo, float hi) { const pg8_f32x2 v = {lo, hi}; const pg8_bf16x2 b = __builtin_convertvector(v, pg8_bf16x2); return __builtin_bit_cast(unsigned, b); }
; __device__ __forceinline__ float ep_sigmoid(float x) { return __builtin_amdgcn_rcpf(1.0f + __expf(-x)); }
; __device__ __forceinline__ float ep_lo(unsigned w) { return __uint_as_float(w << 16); }
; __device__ __forceinline__ float ep_hi(unsigned w) { return __uint_as_float(w & 0xffff0000u); }
;     __device__ __forceinline__ void operator()(const f32x4 (&acc)[2][2][4][2], const Unit& u, int wr, int wc, int fr, int fq) const {
;     ...
;             for (int m = 0; m < 4; ++m) { const size_t row = (size_t)(row0 + ai * HALF + m * 16);
; #pragma unroll
;                 for (int bj = 0; bj < 2; ++bj) { const f32x4 v0 = acc[ai][bj][m][0], v1 = acc[ai][bj][m][1];
;                     const u32x4 yv = *(const u32x4*)(Y + row * ldy + col0 + bj * HALF);
;                     u32x4 w;
;                     w.x = cvt_pk_bf16(ep_lo(yv.x) * ep_sigmoid(v0[0]), ep_hi(yv.x) * ep_sigmoid(v0[1]));
;                     w.y = cvt_pk_bf16(ep_lo(yv.y) * ep_sigmoid(v0[2]), ep_hi(yv.y) * ep_sigmoid(v0[3]));
;                     w.z = cvt_pk_bf16(ep_lo(yv.z) * ep_sigmoid(v1[0]), ep_hi(yv.z) * ep_sigmoid(v1[1]));
;                     w.w = cvt_pk_bf16(ep_lo(yv.w) * ep_sigmoid(v1[2]), ep_hi(yv.w) * ep_sigmoid(v1[3]));
;                     *(u32x4*)(O + row * ldo + ocol0 + col0 + bj * HALF) = w; } }
	v_mov_b64_e32 v[28:29], v[224:225]
	v_mov_b64_e32 v[30:31], v[226:227]
	v_lshlrev_b32_e32 v32, 16, v28
	v_and_b32_e32 v33, 0xffff0000, v28
	v_pk_mul_f32 v[22:23], v[22:23], v[32:33]
	v_lshlrev_b32_e32 v28, 16, v29
	v_cvt_pk_bf16_f32 v22, v22, v23
	v_mul_f32_e32 v23, 0xbfb8aa3b, v24
	v_exp_f32_e32 v23, v23
	v_and_b32_e32 v29, 0xffff0000, v29
	v_add_f32_e32 v23, 1.0, v23
	v_rcp_f32_e32 v24, v23
	v_mul_f32_e32 v23, 0xbfb8aa3b, v25
	v_exp_f32_e32 v23, v23
	s_nop 0
	v_add_f32_e32 v23, 1.0, v23
	v_rcp_f32_e32 v25, v23
	s_nop 0
	v_pk_mul_f32 v[24:25], v[24:25], v[28:29]
	s_nop 0
	v_cvt_pk_bf16_f32 v23, v24, v25
	v_lshlrev_b32_e32 v24, 16, v30
	v_and_b32_e32 v25, 0xffff0000, v30
	v_pk_mul_f32 v[18:19], v[18:19], v[24:25]
	s_nop 0
	v_cvt_pk_bf16_f32 v24, v18, v19
	v_mul_f32_e32 v18, 0xbfb8aa3b, v20
	v_mul_f32_e32 v19, 0xbfb8aa3b, v21
	v_exp_f32_e32 v18, v18
	v_exp_f32_e32 v19, v19
	v_lshlrev_b32_e32 v20, 16, v31
	v_and_b32_e32 v21, 0xffff0000, v31
	v_add_f32_e32 v18, 1.0, v18
	v_add_f32_e32 v19, 1.0, v19
	v_rcp_f32_e32 v18, v18
	v_rcp_f32_e32 v19, v19
	s_nop 0
	v_pk_mul_f32 v[18:19], v[18:19], v[20:21]
	s_nop 0
	v_cvt_pk_bf16_f32 v25, v18, v19
	global_store_dwordx4 v[26:27], v[22:25], off offset:2304
	s_nop 1
	v_add_u32_e32 v24, 0xb0, v142
	v_ashrrev_i32_e32 v25, 31, v24
	v_lshlrev_b64 v[18:19], 11, v[24:25]
	v_lshl_add_u64 v[18:19], s[42:43], 0, v[18:19]
	v_lshl_add_u64 v[18:19], v[18:19], 0, v[140:141]
	s_waitcnt vmcnt(15)
	v_mov_b64_e32 v[20:21], v[228:229]
	v_mov_b64_e32 v[22:23], v[230:231]
	v_lshlrev_b32_e32 v26, 16, v20
	v_and_b32_e32 v27, 0xffff0000, v20
	v_pk_mul_f32 v[14:15], v[14:15], v[26:27]
	s_nop 0
	v_cvt_pk_bf16_f32 v20, v14, v15
	v_mul_f32_e32 v14, 0xbfb8aa3b, v16
	v_mul_f32_e32 v15, 0xbfb8aa3b, v17
	v_exp_f32_e32 v14, v14
	v_exp_f32_e32 v15, v15
	v_lshlrev_b32_e32 v16, 16, v21
	v_and_b32_e32 v17, 0xffff0000, v21
	v_add_f32_e32 v14, 1.0, v14
	v_add_f32_e32 v15, 1.0, v15
	v_rcp_f32_e32 v14, v14
	v_rcp_f32_e32 v15, v15
	s_nop 0
	v_pk_mul_f32 v[14:15], v[14:15], v[16:17]
	s_nop 0
	v_cvt_pk_bf16_f32 v21, v14, v15
	v_lshlrev_b32_e32 v14, 16, v22
	v_and_b32_e32 v15, 0xffff0000, v22
	v_pk_mul_f32 v[10:11], v[10:11], v[14:15]
	s_nop 0
	v_cvt_pk_bf16_f32 v22, v10, v11
	v_mul_f32_e32 v10, 0xbfb8aa3b, v12
	v_mul_f32_e32 v11, 0xbfb8aa3b, v13
	v_exp_f32_e32 v10, v10
	v_exp_f32_e32 v11, v11
	v_lshlrev_b32_e32 v12, 16, v23
	v_and_b32_e32 v13, 0xffff0000, v23
	v_add_f32_e32 v10, 1.0, v10
	v_add_f32_e32 v11, 1.0, v11
	v_rcp_f32_e32 v10, v10
	v_rcp_f32_e32 v11, v11
	s_nop 0
	v_pk_mul_f32 v[10:11], v[10:11], v[12:13]
	s_nop 0
	v_cvt_pk_bf16_f32 v23, v10, v11
	v_lshlrev_b64 v[10:11], 12, v[24:25]
	v_lshl_add_u64 v[10:11], s[46:47], 0, v[10:11]
	v_lshl_add_u64 v[14:15], v[10:11], 0, v[140:141]
	s_waitcnt vmcnt(14)
	v_mov_b64_e32 v[10:11], v[232:233]
	v_mov_b64_e32 v[12:13], v[234:235]
	v_lshlrev_b32_e32 v16, 16, v10
	v_and_b32_e32 v17, 0xffff0000, v10
	v_pk_mul_f32 v[6:7], v[6:7], v[16:17]
	v_lshlrev_b32_e32 v10, 16, v11
	v_cvt_pk_bf16_f32 v6, v6, v7
	v_mul_f32_e32 v7, 0xbfb8aa3b, v8
	v_exp_f32_e32 v7, v7
	v_and_b32_e32 v11, 0xffff0000, v11
	global_store_dwordx4 v[14:15], v[20:23], off offset:2048
	v_add_f32_e32 v7, 1.0, v7
	v_rcp_f32_e32 v8, v7
	v_mul_f32_e32 v7, 0xbfb8aa3b, v9
	v_exp_f32_e32 v7, v7
	s_nop 0
	v_add_f32_e32 v7, 1.0, v7
	v_rcp_f32_e32 v9, v7
	s_nop 0
	v_pk_mul_f32 v[8:9], v[8:9], v[10:11]
	s_nop 0
	v_cvt_pk_bf16_f32 v7, v8, v9
	v_lshlrev_b32_e32 v8, 16, v12
	v_and_b32_e32 v9, 0xffff0000, v12
	v_pk_mul_f32 v[2:3], v[2:3], v[8:9]
	s_nop 0
	v_cvt_pk_bf16_f32 v8, v2, v3
	v_mul_f32_e32 v2, 0xbfb8aa3b, v4
	v_mul_f32_e32 v3, 0xbfb8aa3b, v5
	v_exp_f32_e32 v2, v2
	v_exp_f32_e32 v3, v3
	v_lshlrev_b32_e32 v4, 16, v13
	v_and_b32_e32 v5, 0xffff0000, v13
	v_add_f32_e32 v2, 1.0, v2
	v_add_f32_e32 v3, 1.0, v3
	v_rcp_f32_e32 v2, v2
	v_rcp_f32_e32 v3, v3
	s_nop 0
	v_pk_mul_f32 v[2:3], v[2:3], v[4:5]
	s_nop 0
	v_cvt_pk_bf16_f32 v9, v2, v3
	global_store_dwordx4 v[14:15], v[6:9], off offset:2304
	s_cbranch_vccnz .LBB0_1628
	s_andn2_b64 vcc, exec, s[44:45]
	s_cbranch_vccnz .LBB0_1627
	s_barrier
	s_branch .LBB0_1627

; __device__ __forceinline__ int fresh_lane() { int l; asm volatile("v_mbcnt_lo_u32_b32 %0, -1, 0\n\tv_mbcnt_hi_u32_b32 %0, -1, %0" : "=v"(l)); return l; }
; #define PG8_STAGE(bufoff, gbase, voff) do { _Pragma("unroll") for (int _i = 0; _i < 2; ++_i) \
;         __builtin_amdgcn_global_load_lds((const unsigned*)((const char*)(gbase) + (voff)[_i]), (PG8_LAS unsigned*)(lds + (bufoff) + ldsw + _i * 8192), 16, 0, 0); } while (0)
; #define PG8_WAIT_V(n) asm volatile("s_waitcnt vmcnt(" #n ")" ::: "memory")
; #define PG8_BAR __builtin_amdgcn_s_barrier()
; template <class Epi, class Sched, bool ALIGN_EPI = false, bool SP2 = false, bool F16 = false>
; __device__ __forceinline__ void gemm_phase(PG8_LAS unsigned char* lds, const Gemm g, const Sched& S, const Epi& E) {
;     int tid_ = g.wave * 64 + fresh_lane(); asm volatile("" : "+v"(tid_));   const int tid = tid_, wid = __builtin_amdgcn_readfirstlane(tid >> 6), lane = tid & 63, wr = wid >> 2, wc = wid & 3, fr = lane & 15, fq = lane >> 4;
;     const int K = g.K, nt = K / BK;
;     unsigned voffA[2], voffB[2];
; #pragma unroll
;     for (int i = 0; i < 2; ++i) { int R, C; stage_rc(tid * 16 + i * 8192, R, C); const int Rb = Epi::PERM ? ((R & ~31) + perm32(R & 31)) : R;
;         voffA[i] = (unsigned)(R * K + C) * 2u; voffB[i] = (unsigned)(Rb * K + C) * 2u; }
;     const size_t kstep = (size_t)(BK * 2);
;     const size_t hstep = (size_t)HALF * K * 2;
;     const size_t tstep = 2 * hstep;
;     const unsigned ldsw = (unsigned)wid * 1024u;
;     const int aoff = lds_byte(wr * 64 + fr, fq * 8), boff = lds_byte(wc * 32 + fr, fq * 8);
;     ...
;     if constexpr (SP2) {
;         PG8_STAGE(PG8_SB(0, 0), cB, voffB); PG8_STAGE(PG8_SB(0, 1), cB + hstep, voffB); PG8_STAGE(PG8_SA(0, 0), cA, voffA); PG8_STAGE(PG8_SA(0, 1), cA + hstep, voffA);
;         if (wr == 1) PG8_BAR;
;         PG8_WAIT_V(2); PG8_BAR;
;         PG8_STAGE(PG8_SB(1, 0), cB + kstep, voffB); PG8_STAGE(PG8_SA(1, 0), cA + kstep, voffA); PG8_STAGE(PG8_SB(1, 1), cB + hstep + kstep, voffB);
;         PG8_WAIT_V(6); PG8_BAR;
.LBB0_1810:
	s_add_u32 s10, s8, 0x2ae00000
	v_lshrrev_b32_e32 v18, 1, v16
	s_addc_u32 s11, s9, 0
	v_and_b32_e32 v18, 24, v18
	s_lshl_b32 s13, s13, 5
	v_and_b32_e32 v17, 15, v16
	v_lshlrev_b32_e32 v19, 1, v18
	v_lshlrev_b32_e32 v16, 2, v16
	s_and_b32 s16, s13, 0x60
	s_add_i32 m0, s54, 0x18000
	v_lshl_add_u64 v[8:9], v[8:9], 0, s[24:25]
	v_lshl_or_b32 v142, s14, 6, v17
	v_lshl_or_b32 v17, v17, 6, v19
	s_lshl_b32 s14, s14, 13
	v_and_b32_e32 v16, 32, v16
	s_lshl_b32 s13, s16, 7
	s_waitcnt vmcnt(2)
	s_barrier
	global_load_lds_dwordx4 v[8:9], off
	v_lshl_add_u64 v[6:7], v[6:7], 0, s[24:25]
	s_add_i32 m0, s54, 0x1a000
	s_add_i32 s58, s54, 0x8000
	s_add_i32 s59, s54, 0xa000
	v_bitop3_b32 v19, v17, s14, v16 bitop3:0xde
	global_load_lds_dwordx4 v[6:7], off
	v_lshl_add_u64 v[2:3], v[2:3], 0, s[24:25]
	s_mov_b32 m0, s58
	s_add_u32 s14, s42, 0x80080
	global_load_lds_dwordx4 v[2:3], off
	v_lshl_add_u64 v[2:3], v[4:5], 0, s[24:25]
	s_mov_b32 m0, s59
	s_addc_u32 s15, s43, 0
	global_load_lds_dwordx4 v[2:3], off
	s_add_i32 m0, s54, 0x1c000
	v_lshl_add_u64 v[2:3], s[14:15], 0, v[0:1]
	global_load_lds_dwordx4 v[2:3], off
	v_lshl_add_u64 v[2:3], s[14:15], 0, v[130:131]
	s_add_i32 m0, s54, 0x1e000
	s_cmpk_lt_u32 s12, 0x100
	global_load_lds_dwordx4 v[2:3], off
	v_lshlrev_b32_e32 v2, 15, v14
	v_and_b32_e32 v2, 0xffff0000, v2
	v_lshl_add_u32 v2, v13, 12, v2
	v_and_b32_e32 v3, 1, v14
	v_lshl_or_b32 v2, v3, 6, v2
	v_lshl_add_u32 v136, v15, 1, v2
	v_lshlrev_b32_e32 v2, 15, v10
	v_and_b32_e32 v2, 0xffff0000, v2
	s_waitcnt vmcnt(6)
	v_lshl_add_u32 v2, v11, 12, v2
	v_and_b32_e32 v3, 1, v10
	v_lshl_or_b32 v2, v3, 6, v2
	v_readlane_b32 s14, v254, 24
	v_bitop3_b32 v143, v17, s13, v16 bitop3:0xde
	s_cselect_b64 s[12:13], -1, 0
	s_ashr_i32 s60, s36, 31
	v_or_b32_e32 v144, s16, v18
	v_mov_b32_e32 v137, v1
	v_lshl_add_u32 v138, v12, 1, v2
	v_mov_b32_e32 v139, v1
	s_mov_b32 s61, 0
	v_add_u32_e32 v145, 0, v19
	v_readlane_b32 s62, v254, 23
	s_mov_b32 s63, s14
	s_barrier
	v_readlane_b32 s15, v254, 25
	s_mov_b32 s100, 0
	s_branch .LBB0_1813

; #define PG8_BAR __builtin_amdgcn_s_barrier()
; template <class Epi, class Sched, bool ALIGN_EPI = false, bool SP2 = false, bool F16 = false>
; __device__ __forceinline__ void gemm_phase(PG8_LAS unsigned char* lds, const Gemm g, const Sched& S, const Epi& E) {
;     ...
;         if (!has_next) break;
; #pragma unroll
;         for (int a = 0; a < 2; ++a)
; #pragma unroll
;             for (int b = 0; b < 2; ++b)
; #pragma unroll
;                 for (int m = 0; m < 4; ++m)
; #pragma unroll
;                     for (int n = 0; n < 2; ++n) acc[a][b][m][n] = (f32x4){0.f, 0.f, 0.f, 0.f};
;         cur = nxt; cA = nA; cB = nB; ++ui;
;         if constexpr (ALIGN_EPI) { if (wr == 1) PG8_BAR; }
;     }
.LBB0_1812:
	s_andn2_b64 vcc, exec, s[26:27]
	s_mov_b32 s62, s14
	s_mov_b32 s63, s16
	s_mov_b64 s[42:43], s[20:21]
	s_mov_b64 s[26:27], s[18:19]
	s_cbranch_vccz .LBB0_1822
	s_mov_b32 s100, 2

; #define PG8_STAGE(bufoff, gbase, voff) do { _Pragma("unroll") for (int _i = 0; _i < 2; ++_i) \
;         __builtin_amdgcn_global_load_lds((const unsigned*)((const char*)(gbase) + (voff)[_i]), (PG8_LAS unsigned*)(lds + (bufoff) + ldsw + _i * 8192), 16, 0, 0); } while (0)
; #define PG8_LDA(dst, b, h) do { _Pragma("unroll") for (int m = 0; m < 4; ++m) _Pragma("unroll") for (int k = 0; k < 2; ++k) dst[m][k] = *(const PG8_LAS bf16x8*)(lds + PG8_SA(b, h) + aoff + m * 2048 + k * 1024); } while (0)
; #define PG8_LDB(dst, b, h) do { _Pragma("unroll") for (int n = 0; n < 2; ++n) _Pragma("unroll") for (int k = 0; k < 2; ++k) dst[n][k] = *(const PG8_LAS bf16x8*)(lds + PG8_SB(b, h) + boff + n * 2048 + k * 1024); } while (0)
; #define PG8_MMA(ai, bj, At, Bt) do { __builtin_amdgcn_s_setprio(1); _Pragma("unroll") for (int m = 0; m < 4; ++m) _Pragma("unroll") for (int n = 0; n < 2; ++n) _Pragma("unroll") for (int k = 0; k < 2; ++k) \
;         acc[ai][bj][m][n] = pg8_mma<F16>(Bt[n][k], At[m][k], acc[ai][bj][m][n]); __builtin_amdgcn_s_setprio(0); } while (0)
; #define PG8_WAIT_V(n) asm volatile("s_waitcnt vmcnt(" #n ")" ::: "memory")
; #define PG8_WAIT_L(n) asm volatile("s_waitcnt lgkmcnt(" #n ")" ::: "memory")
; #define PG8_BAR __builtin_amdgcn_s_barrier()
; #define PG8_SCHED __builtin_amdgcn_sched_barrier(0)
; template <class Epi, class Sched, bool ALIGN_EPI = false, bool SP2 = false, bool F16 = false>
; __device__ __forceinline__ void gemm_phase(PG8_LAS unsigned char* lds, const Gemm g, const Sched& S, const Epi& E) {
;     ...
;             PG8_LDB(B0, 0, 0); PG8_LDB(B1, 0, 1); PG8_SCHED; PG8_LDA(At, 0, 0); PG8_STAGE(PG8_SA(1, 1), a1 + hstep, voffA);
;             PG8_WAIT_V(8); PG8_WAIT_L(0); PG8_BAR; PG8_MMA(0, 0, At, B0); PG8_MMA(0, 1, At, B1); PG8_BAR; PG8_SCHED;
.LBB0_1816:
	s_add_u32 s42, s26, 0xfff80080
	s_addc_u32 s43, s27, -1
	s_add_i32 s69, 0, 0x10000
	s_cmp_eq_u32 s68, 28
	s_cselect_b32 s45, s17, s43
	s_cselect_b32 s44, s64, s42
	v_add_u32_e32 v140, s69, v143
	s_cselect_b32 s43, s15, s67
	s_cselect_b32 s42, s65, s66
	s_add_i32 s72, 0, 0x14000
	ds_read_b128 v[146:149], v140
	ds_read_b128 v[150:153], v140 offset:1024
	ds_read_b128 v[154:157], v140 offset:2048
	ds_read_b128 v[158:161], v140 offset:3072
	v_add_u32_e32 v140, s72, v143
	ds_read_b128 v[162:165], v140
	ds_read_b128 v[166:169], v140 offset:1024
	ds_read_b128 v[170:173], v140 offset:2048
	ds_read_b128 v[174:177], v140 offset:3072
	v_lshl_add_u64 v[140:141], s[26:27], 0, v[136:137]
	s_add_i32 m0, s54, 0xc000
	ds_read_b128 v[178:181], v145
	ds_read_b128 v[182:185], v145 offset:1024
	ds_read_b128 v[186:189], v145 offset:2048
	ds_read_b128 v[190:193], v145 offset:3072
	ds_read_b128 v[194:197], v145 offset:4096
	ds_read_b128 v[198:201], v145 offset:5120
	ds_read_b128 v[202:205], v145 offset:6144
	ds_read_b128 v[206:209], v145 offset:7168
	global_load_lds_dwordx4 v[140:141], off
	v_lshl_add_u64 v[140:141], s[26:27], 0, v[138:139]
	s_add_i32 m0, s54, 0xe000
	s_nop 0
	global_load_lds_dwordx4 v[140:141], off
	s_cmp_eq_u32 s100, 0
	s_cbranch_scc1 .Lur_up_n0
	s_sub_u32 s100, s100, 1
	s_waitcnt vmcnt(16)
	s_branch .Lur_up_d0

; #define PG8_STAGE(bufoff, gbase, voff) do { _Pragma("unroll") for (int _i = 0; _i < 2; ++_i) \
;         __builtin_amdgcn_global_load_lds((const unsigned*)((const char*)(gbase) + (voff)[_i]), (PG8_LAS unsigned*)(lds + (bufoff) + ldsw + _i * 8192), 16, 0, 0); } while (0)
; #define PG8_LDA(dst, b, h) do { _Pragma("unroll") for (int m = 0; m < 4; ++m) _Pragma("unroll") for (int k = 0; k < 2; ++k) dst[m][k] = *(const PG8_LAS bf16x8*)(lds + PG8_SA(b, h) + aoff + m * 2048 + k * 1024); } while (0)
; #define PG8_MMA(ai, bj, At, Bt) do { __builtin_amdgcn_s_setprio(1); _Pragma("unroll") for (int m = 0; m < 4; ++m) _Pragma("unroll") for (int n = 0; n < 2; ++n) _Pragma("unroll") for (int k = 0; k < 2; ++k) \
;         acc[ai][bj][m][n] = pg8_mma<F16>(Bt[n][k], At[m][k], acc[ai][bj][m][n]); __builtin_amdgcn_s_setprio(0); } while (0)
; #define PG8_WAIT_V(n) asm volatile("s_waitcnt vmcnt(" #n ")" ::: "memory")
; #define PG8_WAIT_L(n) asm volatile("s_waitcnt lgkmcnt(" #n ")" ::: "memory")
; #define PG8_BAR __builtin_amdgcn_s_barrier()
; #define PG8_SCHED __builtin_amdgcn_sched_barrier(0)
; template <class Epi, class Sched, bool ALIGN_EPI = false, bool SP2 = false, bool F16 = false>
; __device__ __forceinline__ void gemm_phase(PG8_LAS unsigned char* lds, const Gemm g, const Sched& S, const Epi& E) {
;     ...
;             PG8_WAIT_V(8); PG8_WAIT_L(0); PG8_BAR; PG8_MMA(0, 0, At, B0); PG8_MMA(0, 1, At, B1); PG8_BAR; PG8_SCHED;
;             PG8_LDA(At, 0, 1); PG8_STAGE(PG8_SB(0, 0), b2, voffB); PG8_STAGE(PG8_SB(0, 1), b2 + hstep, voffB); PG8_STAGE(PG8_SA(0, 0), a2, voffA);
.Lur_up_d0:
	s_waitcnt lgkmcnt(0)
	s_barrier
	s_setprio 1
	s_waitcnt lgkmcnt(0)
	v_mfma_f32_16x16x32_bf16 v[126:129], v[146:149], v[178:181], v[126:129]
	v_mfma_f32_16x16x32_bf16 v[122:125], v[154:157], v[178:181], v[122:125]
	v_mfma_f32_16x16x32_bf16 v[110:113], v[146:149], v[186:189], v[110:113]
	v_mfma_f32_16x16x32_bf16 v[106:109], v[154:157], v[186:189], v[106:109]
	v_mfma_f32_16x16x32_bf16 v[94:97], v[146:149], v[194:197], v[94:97]
	v_mfma_f32_16x16x32_bf16 v[90:93], v[154:157], v[194:197], v[90:93]
	v_mfma_f32_16x16x32_bf16 v[78:81], v[146:149], v[202:205], v[78:81]
	v_mfma_f32_16x16x32_bf16 v[74:77], v[154:157], v[202:205], v[74:77]
	v_mfma_f32_16x16x32_bf16 v[126:129], v[150:153], v[182:185], v[126:129]
	v_mfma_f32_16x16x32_bf16 v[122:125], v[158:161], v[182:185], v[122:125]
	v_mfma_f32_16x16x32_bf16 v[110:113], v[150:153], v[190:193], v[110:113]
	v_mfma_f32_16x16x32_bf16 v[106:109], v[158:161], v[190:193], v[106:109]
	v_mfma_f32_16x16x32_bf16 v[94:97], v[150:153], v[198:201], v[94:97]
	v_mfma_f32_16x16x32_bf16 v[90:93], v[158:161], v[198:201], v[90:93]
	v_mfma_f32_16x16x32_bf16 v[78:81], v[150:153], v[206:209], v[78:81]
	v_mfma_f32_16x16x32_bf16 v[74:77], v[158:161], v[206:209], v[74:77]
	s_setprio 0
	s_setprio 1
	v_mfma_f32_16x16x32_bf16 v[118:121], v[162:165], v[178:181], v[118:121]
	v_mfma_f32_16x16x32_bf16 v[114:117], v[170:173], v[178:181], v[114:117]
	v_mfma_f32_16x16x32_bf16 v[102:105], v[162:165], v[186:189], v[102:105]
	v_mfma_f32_16x16x32_bf16 v[98:101], v[170:173], v[186:189], v[98:101]
	v_mfma_f32_16x16x32_bf16 v[86:89], v[162:165], v[194:197], v[86:89]
	v_mfma_f32_16x16x32_bf16 v[82:85], v[170:173], v[194:197], v[82:85]
	v_mfma_f32_16x16x32_bf16 v[70:73], v[162:165], v[202:205], v[70:73]
	v_mfma_f32_16x16x32_bf16 v[66:69], v[170:173], v[202:205], v[66:69]
	v_mfma_f32_16x16x32_bf16 v[118:121], v[166:169], v[182:185], v[118:121]
	v_mfma_f32_16x16x32_bf16 v[114:117], v[174:177], v[182:185], v[114:117]
	v_mfma_f32_16x16x32_bf16 v[102:105], v[166:169], v[190:193], v[102:105]
	v_mfma_f32_16x16x32_bf16 v[98:101], v[174:177], v[190:193], v[98:101]
	v_mfma_f32_16x16x32_bf16 v[86:89], v[166:169], v[198:201], v[86:89]
	v_mfma_f32_16x16x32_bf16 v[82:85], v[174:177], v[198:201], v[82:85]
	v_mfma_f32_16x16x32_bf16 v[70:73], v[166:169], v[206:209], v[70:73]
	v_mfma_f32_16x16x32_bf16 v[66:69], v[174:177], v[206:209], v[66:69]
	s_setprio 0
	s_barrier
	s_add_i32 s69, s69, s53
	v_lshl_add_u64 v[140:141], s[42:43], 0, v[0:1]
	s_mov_b32 m0, s69
	ds_read_b128 v[178:181], v145 offset:16384
	ds_read_b128 v[182:185], v145 offset:17408
	ds_read_b128 v[186:189], v145 offset:18432
	ds_read_b128 v[190:193], v145 offset:19456
	ds_read_b128 v[194:197], v145 offset:20480
	ds_read_b128 v[198:201], v145 offset:21504
	ds_read_b128 v[202:205], v145 offset:22528
	ds_read_b128 v[206:209], v145 offset:23552
	global_load_lds_dwordx4 v[140:141], off
	s_add_i32 m0, s69, 0x2000
	s_add_u32 s70, s42, 0x80000
	v_lshl_add_u64 v[210:211], s[42:43], 0, v[130:131]
	s_addc_u32 s71, s43, 0
	s_add_i32 s69, s72, s53
	global_load_lds_dwordx4 v[210:211], off
	v_lshl_add_u64 v[212:213], s[70:71], 0, v[0:1]
	s_mov_b32 m0, s69
	v_lshl_add_u64 v[214:215], s[44:45], 0, v[132:133]
	global_load_lds_dwordx4 v[212:213], off
	v_lshl_add_u64 v[212:213], s[70:71], 0, v[130:131]
	s_add_i32 m0, s69, 0x2000
	s_nop 0
	global_load_lds_dwordx4 v[212:213], off
	v_lshl_add_u64 v[212:213], s[44:45], 0, v[134:135]
	s_mov_b32 m0, s54
	s_nop 0
	global_load_lds_dwordx4 v[212:213], off
	s_mov_b32 m0, s55
	s_nop 0
	global_load_lds_dwordx4 v[214:215], off
	s_cmp_eq_u32 s100, 0
	s_cbranch_scc1 .Lur_up_n1
	s_sub_u32 s100, s100, 1
	s_waitcnt vmcnt(16)
	s_branch .Lur_up_d1

; #define PG8_STAGE(bufoff, gbase, voff) do { _Pragma("unroll") for (int _i = 0; _i < 2; ++_i) \
;         __builtin_amdgcn_global_load_lds((const unsigned*)((const char*)(gbase) + (voff)[_i]), (PG8_LAS unsigned*)(lds + (bufoff) + ldsw + _i * 8192), 16, 0, 0); } while (0)
; #define PG8_LDA(dst, b, h) do { _Pragma("unroll") for (int m = 0; m < 4; ++m) _Pragma("unroll") for (int k = 0; k < 2; ++k) dst[m][k] = *(const PG8_LAS bf16x8*)(lds + PG8_SA(b, h) + aoff + m * 2048 + k * 1024); } while (0)
; #define PG8_LDB(dst, b, h) do { _Pragma("unroll") for (int n = 0; n < 2; ++n) _Pragma("unroll") for (int k = 0; k < 2; ++k) dst[n][k] = *(const PG8_LAS bf16x8*)(lds + PG8_SB(b, h) + boff + n * 2048 + k * 1024); } while (0)
; #define PG8_MMA(ai, bj, At, Bt) do { __builtin_amdgcn_s_setprio(1); _Pragma("unroll") for (int m = 0; m < 4; ++m) _Pragma("unroll") for (int n = 0; n < 2; ++n) _Pragma("unroll") for (int k = 0; k < 2; ++k) \
;         acc[ai][bj][m][n] = pg8_mma<F16>(Bt[n][k], At[m][k], acc[ai][bj][m][n]); __builtin_amdgcn_s_setprio(0); } while (0)
; #define PG8_WAIT_V(n) asm volatile("s_waitcnt vmcnt(" #n ")" ::: "memory")
; #define PG8_WAIT_L(n) asm volatile("s_waitcnt lgkmcnt(" #n ")" ::: "memory")
; #define PG8_BAR __builtin_amdgcn_s_barrier()
; #define PG8_SCHED __builtin_amdgcn_sched_barrier(0)
; template <class Epi, class Sched, bool ALIGN_EPI = false, bool SP2 = false, bool F16 = false>
; __device__ __forceinline__ void gemm_phase(PG8_LAS unsigned char* lds, const Gemm g, const Sched& S, const Epi& E) {
;     ...
;             PG8_WAIT_V(8); PG8_WAIT_L(0); PG8_BAR; PG8_MMA(1, 0, At, B0); PG8_MMA(1, 1, At, B1); PG8_BAR; PG8_SCHED;
;             PG8_LDB(B0, 1, 0); PG8_LDB(B1, 1, 1); PG8_SCHED; PG8_LDA(At, 1, 0); PG8_STAGE(PG8_SA(0, 1), a2 + hstep, voffA);
;             PG8_WAIT_V(8); PG8_WAIT_L(0); PG8_BAR; PG8_MMA(0, 0, At, B0); PG8_MMA(0, 1, At, B1); PG8_BAR; PG8_SCHED;
.Lur_up_d1:
	s_waitcnt lgkmcnt(0)
	s_barrier
	s_setprio 1
	s_waitcnt lgkmcnt(0)
	v_mfma_f32_16x16x32_bf16 v[62:65], v[146:149], v[178:181], v[62:65]
	v_mfma_f32_16x16x32_bf16 v[58:61], v[154:157], v[178:181], v[58:61]
	v_mfma_f32_16x16x32_bf16 v[46:49], v[146:149], v[186:189], v[46:49]
	v_mfma_f32_16x16x32_bf16 v[42:45], v[154:157], v[186:189], v[42:45]
	v_mfma_f32_16x16x32_bf16 v[30:33], v[146:149], v[194:197], v[30:33]
	v_mfma_f32_16x16x32_bf16 v[26:29], v[154:157], v[194:197], v[26:29]
	v_mfma_f32_16x16x32_bf16 v[14:17], v[146:149], v[202:205], v[14:17]
	v_mfma_f32_16x16x32_bf16 v[10:13], v[154:157], v[202:205], v[10:13]
	v_mfma_f32_16x16x32_bf16 v[62:65], v[150:153], v[182:185], v[62:65]
	v_mfma_f32_16x16x32_bf16 v[58:61], v[158:161], v[182:185], v[58:61]
	v_mfma_f32_16x16x32_bf16 v[46:49], v[150:153], v[190:193], v[46:49]
	v_mfma_f32_16x16x32_bf16 v[42:45], v[158:161], v[190:193], v[42:45]
	v_mfma_f32_16x16x32_bf16 v[30:33], v[150:153], v[198:201], v[30:33]
	v_mfma_f32_16x16x32_bf16 v[26:29], v[158:161], v[198:201], v[26:29]
	v_mfma_f32_16x16x32_bf16 v[14:17], v[150:153], v[206:209], v[14:17]
	v_mfma_f32_16x16x32_bf16 v[10:13], v[158:161], v[206:209], v[10:13]
	s_setprio 0
	s_setprio 1
	v_mfma_f32_16x16x32_bf16 v[54:57], v[162:165], v[178:181], v[54:57]
	v_mfma_f32_16x16x32_bf16 v[50:53], v[170:173], v[178:181], v[50:53]
	v_mfma_f32_16x16x32_bf16 v[38:41], v[162:165], v[186:189], v[38:41]
	v_mfma_f32_16x16x32_bf16 v[34:37], v[170:173], v[186:189], v[34:37]
	v_mfma_f32_16x16x32_bf16 v[22:25], v[162:165], v[194:197], v[22:25]
	v_mfma_f32_16x16x32_bf16 v[18:21], v[170:173], v[194:197], v[18:21]
	v_mfma_f32_16x16x32_bf16 v[6:9], v[162:165], v[202:205], v[6:9]
	v_mfma_f32_16x16x32_bf16 v[2:5], v[170:173], v[202:205], v[2:5]
	v_mfma_f32_16x16x32_bf16 v[54:57], v[166:169], v[182:185], v[54:57]
	v_mfma_f32_16x16x32_bf16 v[50:53], v[174:177], v[182:185], v[50:53]
	v_mfma_f32_16x16x32_bf16 v[38:41], v[166:169], v[190:193], v[38:41]
	v_mfma_f32_16x16x32_bf16 v[34:37], v[174:177], v[190:193], v[34:37]
	v_mfma_f32_16x16x32_bf16 v[22:25], v[166:169], v[198:201], v[22:25]
	v_mfma_f32_16x16x32_bf16 v[18:21], v[174:177], v[198:201], v[18:21]
	v_mfma_f32_16x16x32_bf16 v[6:9], v[166:169], v[206:209], v[6:9]
	v_mfma_f32_16x16x32_bf16 v[2:5], v[174:177], v[206:209], v[2:5]
	s_setprio 0
	s_barrier
	s_add_i32 s69, 0, 0x18000
	s_add_i32 s70, 0, 0x1c000
	v_add_u32_e32 v158, s69, v143
	v_add_u32_e32 v174, s70, v143
	ds_read_b128 v[146:149], v158
	ds_read_b128 v[150:153], v158 offset:1024
	ds_read_b128 v[154:157], v158 offset:2048
	ds_read_b128 v[158:161], v158 offset:3072
	ds_read_b128 v[162:165], v174
	ds_read_b128 v[166:169], v174 offset:1024
	ds_read_b128 v[170:173], v174 offset:2048
	ds_read_b128 v[174:177], v174 offset:3072
	s_add_u32 s44, s44, 0x80000
	s_addc_u32 s45, s45, 0
	s_mov_b32 m0, s56
	v_lshl_add_u64 v[220:221], s[44:45], 0, v[134:135]
	ds_read_b128 v[178:181], v145 offset:32768
	ds_read_b128 v[182:185], v145 offset:33792
	ds_read_b128 v[186:189], v145 offset:34816
	ds_read_b128 v[190:193], v145 offset:35840
	ds_read_b128 v[194:197], v145 offset:36864
	ds_read_b128 v[198:201], v145 offset:37888
	ds_read_b128 v[202:205], v145 offset:38912
	ds_read_b128 v[206:209], v145 offset:39936
	global_load_lds_dwordx4 v[220:221], off
	v_lshl_add_u64 v[220:221], s[44:45], 0, v[132:133]
	s_mov_b32 m0, s57
	s_nop 0
	global_load_lds_dwordx4 v[220:221], off
	s_waitcnt vmcnt(8)
	s_waitcnt lgkmcnt(0)
	s_barrier
	s_setprio 1
	s_waitcnt lgkmcnt(0)
	v_mfma_f32_16x16x32_bf16 v[126:129], v[146:149], v[178:181], v[126:129]
	v_mfma_f32_16x16x32_bf16 v[122:125], v[154:157], v[178:181], v[122:125]
	v_mfma_f32_16x16x32_bf16 v[110:113], v[146:149], v[186:189], v[110:113]
	v_mfma_f32_16x16x32_bf16 v[106:109], v[154:157], v[186:189], v[106:109]
	v_mfma_f32_16x16x32_bf16 v[94:97], v[146:149], v[194:197], v[94:97]
	v_mfma_f32_16x16x32_bf16 v[90:93], v[154:157], v[194:197], v[90:93]
	v_mfma_f32_16x16x32_bf16 v[78:81], v[146:149], v[202:205], v[78:81]
	v_mfma_f32_16x16x32_bf16 v[74:77], v[154:157], v[202:205], v[74:77]
	v_mfma_f32_16x16x32_bf16 v[126:129], v[150:153], v[182:185], v[126:129]
	v_mfma_f32_16x16x32_bf16 v[122:125], v[158:161], v[182:185], v[122:125]
	v_mfma_f32_16x16x32_bf16 v[110:113], v[150:153], v[190:193], v[110:113]
	v_mfma_f32_16x16x32_bf16 v[106:109], v[158:161], v[190:193], v[106:109]
	v_mfma_f32_16x16x32_bf16 v[94:97], v[150:153], v[198:201], v[94:97]
	v_mfma_f32_16x16x32_bf16 v[90:93], v[158:161], v[198:201], v[90:93]
	v_mfma_f32_16x16x32_bf16 v[78:81], v[150:153], v[206:209], v[78:81]
	v_mfma_f32_16x16x32_bf16 v[74:77], v[158:161], v[206:209], v[74:77]
	s_setprio 0
	s_setprio 1
	v_mfma_f32_16x16x32_bf16 v[118:121], v[162:165], v[178:181], v[118:121]
	v_mfma_f32_16x16x32_bf16 v[114:117], v[170:173], v[178:181], v[114:117]
	v_mfma_f32_16x16x32_bf16 v[102:105], v[162:165], v[186:189], v[102:105]
	v_mfma_f32_16x16x32_bf16 v[98:101], v[170:173], v[186:189], v[98:101]
	v_mfma_f32_16x16x32_bf16 v[86:89], v[162:165], v[194:197], v[86:89]
	v_mfma_f32_16x16x32_bf16 v[82:85], v[170:173], v[194:197], v[82:85]
	v_mfma_f32_16x16x32_bf16 v[70:73], v[162:165], v[202:205], v[70:73]
	v_mfma_f32_16x16x32_bf16 v[66:69], v[170:173], v[202:205], v[66:69]
	v_mfma_f32_16x16x32_bf16 v[118:121], v[166:169], v[182:185], v[118:121]
	v_mfma_f32_16x16x32_bf16 v[114:117], v[174:177], v[182:185], v[114:117]
	v_mfma_f32_16x16x32_bf16 v[102:105], v[166:169], v[190:193], v[102:105]
	v_mfma_f32_16x16x32_bf16 v[98:101], v[174:177], v[190:193], v[98:101]
	v_mfma_f32_16x16x32_bf16 v[86:89], v[166:169], v[198:201], v[86:89]
	v_mfma_f32_16x16x32_bf16 v[82:85], v[174:177], v[198:201], v[82:85]
	v_mfma_f32_16x16x32_bf16 v[70:73], v[166:169], v[206:209], v[70:73]
	v_mfma_f32_16x16x32_bf16 v[66:69], v[174:177], v[206:209], v[66:69]
	s_setprio 0
	s_barrier
; #define PG8_STAGE(bufoff, gbase, voff) do { _Pragma("unroll") for (int _i = 0; _i < 2; ++_i) \
;         __builtin_amdgcn_global_load_lds((const unsigned*)((const char*)(gbase) + (voff)[_i]), (PG8_LAS unsigned*)(lds + (bufoff) + ldsw + _i * 8192), 16, 0, 0); } while (0)
; #define PG8_LDA(dst, b, h) do { _Pragma("unroll") for (int m = 0; m < 4; ++m) _Pragma("unroll") for (int k = 0; k < 2; ++k) dst[m][k] = *(const PG8_LAS bf16x8*)(lds + PG8_SA(b, h) + aoff + m * 2048 + k * 1024); } while (0)
; #define PG8_MMA(ai, bj, At, Bt) do { __builtin_amdgcn_s_setprio(1); _Pragma("unroll") for (int m = 0; m < 4; ++m) _Pragma("unroll") for (int n = 0; n < 2; ++n) _Pragma("unroll") for (int k = 0; k < 2; ++k) \
;         acc[ai][bj][m][n] = pg8_mma<F16>(Bt[n][k], At[m][k], acc[ai][bj][m][n]); __builtin_amdgcn_s_setprio(0); } while (0)
; #define PG8_WAIT_V(n) asm volatile("s_waitcnt vmcnt(" #n ")" ::: "memory")
; #define PG8_WAIT_L(n) asm volatile("s_waitcnt lgkmcnt(" #n ")" ::: "memory")
; #define PG8_BAR __builtin_amdgcn_s_barrier()
; #define PG8_SCHED __builtin_amdgcn_sched_barrier(0)
; template <class Epi, class Sched, bool ALIGN_EPI = false, bool SP2 = false, bool F16 = false>
; __device__ __forceinline__ void gemm_phase(PG8_LAS unsigned char* lds, const Gemm g, const Sched& S, const Epi& E) {
;     ...
;             PG8_LDA(At, 1, 1); PG8_STAGE(PG8_SB(1, 0), b3, voffB); PG8_STAGE(PG8_SB(1, 1), b3 + hstep, voffB); PG8_STAGE(PG8_SA(1, 0), a3, voffA);
;             PG8_WAIT_V(8); PG8_WAIT_L(0); PG8_BAR; PG8_MMA(1, 0, At, B0); PG8_MMA(1, 1, At, B1); PG8_BAR; PG8_SCHED;
;     ...
;         if constexpr (ALIGN_EPI) { if (wr == 0) PG8_BAR; }
	s_add_i32 s44, s69, s53
	v_lshl_add_u64 v[140:141], v[140:141], 0, s[24:25]
	s_mov_b32 m0, s44
	ds_read_b128 v[178:181], v145 offset:49152
	ds_read_b128 v[182:185], v145 offset:50176
	ds_read_b128 v[186:189], v145 offset:51200
	ds_read_b128 v[190:193], v145 offset:52224
	ds_read_b128 v[194:197], v145 offset:53248
	ds_read_b128 v[198:201], v145 offset:54272
	ds_read_b128 v[202:205], v145 offset:55296
	ds_read_b128 v[206:209], v145 offset:56320
	global_load_lds_dwordx4 v[140:141], off
	s_add_i32 m0, s44, 0x2000
	s_add_u32 s42, s42, 0x80080
	v_lshl_add_u64 v[140:141], v[210:211], 0, s[24:25]
	s_addc_u32 s43, s43, 0
	s_add_i32 s44, s70, s53
	global_load_lds_dwordx4 v[140:141], off
	v_lshl_add_u64 v[140:141], s[42:43], 0, v[0:1]
	s_mov_b32 m0, s44
	s_nop 0
	global_load_lds_dwordx4 v[140:141], off
	v_lshl_add_u64 v[140:141], s[42:43], 0, v[130:131]
	s_add_i32 m0, s44, 0x2000
	s_nop 0
	global_load_lds_dwordx4 v[140:141], off
	v_lshl_add_u64 v[140:141], v[212:213], 0, s[24:25]
	s_mov_b32 m0, s58
	s_nop 0
	global_load_lds_dwordx4 v[140:141], off
	v_lshl_add_u64 v[140:141], v[214:215], 0, s[24:25]
	s_mov_b32 m0, s59
	s_nop 0
	global_load_lds_dwordx4 v[140:141], off
	s_waitcnt vmcnt(8)
	s_waitcnt lgkmcnt(0)
	s_barrier
	s_setprio 1
	s_waitcnt lgkmcnt(0)
	v_mfma_f32_16x16x32_bf16 v[62:65], v[146:149], v[178:181], v[62:65]
	v_mfma_f32_16x16x32_bf16 v[58:61], v[154:157], v[178:181], v[58:61]
	v_mfma_f32_16x16x32_bf16 v[46:49], v[146:149], v[186:189], v[46:49]
	v_mfma_f32_16x16x32_bf16 v[42:45], v[154:157], v[186:189], v[42:45]
	v_mfma_f32_16x16x32_bf16 v[30:33], v[146:149], v[194:197], v[30:33]
	v_mfma_f32_16x16x32_bf16 v[26:29], v[154:157], v[194:197], v[26:29]
	v_mfma_f32_16x16x32_bf16 v[14:17], v[146:149], v[202:205], v[14:17]
	v_mfma_f32_16x16x32_bf16 v[10:13], v[154:157], v[202:205], v[10:13]
	v_mfma_f32_16x16x32_bf16 v[62:65], v[150:153], v[182:185], v[62:65]
	v_mfma_f32_16x16x32_bf16 v[58:61], v[158:161], v[182:185], v[58:61]
	v_mfma_f32_16x16x32_bf16 v[46:49], v[150:153], v[190:193], v[46:49]
	v_mfma_f32_16x16x32_bf16 v[42:45], v[158:161], v[190:193], v[42:45]
	v_mfma_f32_16x16x32_bf16 v[30:33], v[150:153], v[198:201], v[30:33]
	v_mfma_f32_16x16x32_bf16 v[26:29], v[158:161], v[198:201], v[26:29]
	v_mfma_f32_16x16x32_bf16 v[14:17], v[150:153], v[206:209], v[14:17]
	v_mfma_f32_16x16x32_bf16 v[10:13], v[158:161], v[206:209], v[10:13]
	s_setprio 0
	s_setprio 1
	v_mfma_f32_16x16x32_bf16 v[54:57], v[162:165], v[178:181], v[54:57]
	v_mfma_f32_16x16x32_bf16 v[50:53], v[170:173], v[178:181], v[50:53]
	v_mfma_f32_16x16x32_bf16 v[38:41], v[162:165], v[186:189], v[38:41]
	v_mfma_f32_16x16x32_bf16 v[34:37], v[170:173], v[186:189], v[34:37]
	v_mfma_f32_16x16x32_bf16 v[22:25], v[162:165], v[194:197], v[22:25]
	v_mfma_f32_16x16x32_bf16 v[18:21], v[170:173], v[194:197], v[18:21]
	v_mfma_f32_16x16x32_bf16 v[6:9], v[162:165], v[202:205], v[6:9]
	v_mfma_f32_16x16x32_bf16 v[2:5], v[170:173], v[202:205], v[2:5]
	v_mfma_f32_16x16x32_bf16 v[54:57], v[166:169], v[182:185], v[54:57]
	v_mfma_f32_16x16x32_bf16 v[50:53], v[174:177], v[182:185], v[50:53]
	v_mfma_f32_16x16x32_bf16 v[38:41], v[166:169], v[190:193], v[38:41]
	v_mfma_f32_16x16x32_bf16 v[34:37], v[174:177], v[190:193], v[34:37]
	v_mfma_f32_16x16x32_bf16 v[22:25], v[166:169], v[198:201], v[22:25]
	v_mfma_f32_16x16x32_bf16 v[18:21], v[174:177], v[198:201], v[18:21]
	v_mfma_f32_16x16x32_bf16 v[6:9], v[166:169], v[206:209], v[6:9]
	v_mfma_f32_16x16x32_bf16 v[2:5], v[174:177], v[206:209], v[2:5]
	s_setprio 0
	s_barrier
	s_add_i32 s68, s68, 2
	s_add_u32 s26, s26, 0x100
	s_addc_u32 s27, s27, 0
	s_add_u32 s66, s66, 0x100
	s_addc_u32 s67, s67, 0
	s_cmp_gt_u32 s68, 29
	s_cbranch_scc0 .LBB0_1816
	s_and_b64 vcc, exec, s[12:13]
	s_cbranch_vccz .LBB0_1819
	s_barrier

; __global__ void __launch_bounds__(512, 2) fwd(Args args) {
;     extern __shared__ __attribute__((aligned(16))) unsigned char lds_raw[];
	.amdhsa_kernel _Z3fwd4Args
		.amdhsa_group_segment_fixed_size 0
		.amdhsa_private_segment_fixed_size 0
		.amdhsa_kernarg_size 560
		.amdhsa_user_sgpr_count 2
		.amdhsa_user_sgpr_dispatch_ptr 0
		.amdhsa_user_sgpr_queue_ptr 0
		.amdhsa_user_sgpr_kernarg_segment_ptr 1
		.amdhsa_user_sgpr_dispatch_id 0
		.amdhsa_user_sgpr_kernarg_preload_length 0
		.amdhsa_user_sgpr_kernarg_preload_offset 0
		.amdhsa_user_sgpr_private_segment_size 0
		.amdhsa_uses_dynamic_stack 0
		.amdhsa_enable_private_segment 0
		.amdhsa_system_sgpr_workgroup_id_x 1
		.amdhsa_system_sgpr_workgroup_id_y 0
		.amdhsa_system_sgpr_workgroup_id_z 0
		.amdhsa_system_sgpr_workgroup_info 0
		.amdhsa_system_vgpr_workitem_id 0
		.amdhsa_next_free_vgpr 256
		.amdhsa_next_free_sgpr 102
		.amdhsa_accum_offset 256
		.amdhsa_reserve_vcc 1
		.amdhsa_float_round_mode_32 0
		.amdhsa_float_round_mode_16_64 0
		.amdhsa_float_denorm_mode_32 3
		.amdhsa_float_denorm_mode_16_64 3
		.amdhsa_dx10_clamp 1
		.amdhsa_ieee_mode 1
		.amdhsa_fp16_overflow 0
		.amdhsa_tg_split 0
		.amdhsa_exception_fp_ieee_invalid_op 0
		.amdhsa_exception_fp_denorm_src 0
		.amdhsa_exception_fp_ieee_div_zero 0
		.amdhsa_exception_fp_ieee_overflow 0
		.amdhsa_exception_fp_ieee_underflow 0
		.amdhsa_exception_fp_ieee_inexact 0
		.amdhsa_exception_int_div_zero 0
	.end_amdhsa_kernel

; __global__ void __launch_bounds__(512, 2) fwd(Args args) {
;     extern __shared__ __attribute__((aligned(16))) unsigned char lds_raw[];
amdhsa.kernels:
  - .agpr_count:     0
    .args:
      - .offset:         0
        .size:           304
        .value_kind:     by_value
      - .offset:         304
        .size:           4
        .value_kind:     hidden_block_count_x
      - .offset:         308
        .size:           4
        .value_kind:     hidden_block_count_y
      - .offset:         312
        .size:           4
        .value_kind:     hidden_block_count_z
      - .offset:         316
        .size:           2
        .value_kind:     hidden_group_size_x
      - .offset:         318
        .size:           2
        .value_kind:     hidden_group_size_y
      - .offset:         320
        .size:           2
        .value_kind:     hidden_group_size_z
      - .offset:         322
        .size:           2
        .value_kind:     hidden_remainder_x
      - .offset:         324
        .size:           2
        .value_kind:     hidden_remainder_y
      - .offset:         326
        .size:           2
        .value_kind:     hidden_remainder_z
      - .offset:         344
        .size:           8
        .value_kind:     hidden_global_offset_x
      - .offset:         352
        .size:           8
        .value_kind:     hidden_global_offset_y
      - .offset:         360
        .size:           8
        .value_kind:     hidden_global_offset_z
      - .offset:         368
        .size:           2
        .value_kind:     hidden_grid_dims
      - .offset:         424
        .size:           4
        .value_kind:     hidden_dynamic_lds_size
    .group_segment_fixed_size: 0
    .kernarg_segment_align: 8
    .kernarg_segment_size: 560
    .language:       OpenCL C
    .language_version:
      - 2
      - 0
    .max_flat_workgroup_size: 512
    .name:           _Z3fwd4Args
    .private_segment_fixed_size: 0
    .sgpr_count:     108
    .sgpr_spill_count: 219
    .symbol:         _Z3fwd4Args.kd
    .uniform_work_group_size: 1
    .uses_dynamic_stack: false
    .vgpr_count:     256
    .vgpr_spill_count: 0
    .wavefront_size: 64
